# batched x loads in EpiResid epilogues (mix + MLP down): 16 loads, one wait, then fma/store
# speedup vs baseline: 1.0044x; 1.0044x over previous
; __device__ __forceinline__ unsigned cvt_pk_bf16(float lo, float hi) { f32x2_t v = {lo, hi}; bf16x2_t b = __builtin_convertvector(v, bf16x2_t); return __builtin_bit_cast(unsigned, b); }
; __device__ __forceinline__ float bflo(unsigned w) { return __uint_as_float(w << 16); }
; __device__ __forceinline__ float bfhi(unsigned w) { return __uint_as_float(w & 0xffff0000u); }
;     __device__ __forceinline__ void operator()(const f32x4 (&acc)[2][2][4][2], const Unit& u, int wr, int wc, int fr, int fq) const {
;         const int col0 = u.pn * BM + wc * 32 + 8 * fq; const int row0 = u.pm * BM + wr * 64 + fr;
;         const float* gp = gate + (size_t)(u.pm >> 3) * 6144 + col0;
;         f32x4 gv[2][2];
; #pragma unroll
;         for (int bj = 0; bj < 2; ++bj)
; #pragma unroll
;             for (int n = 0; n < 2; ++n) gv[bj][n] = *(const f32x4*)(gp + bj * HALF + n * 4);
; #pragma unroll
;         for (int ai = 0; ai < 2; ++ai)
; #pragma unroll
;             for (int m = 0; m < 4; ++m) { const size_t off = (size_t)(row0 + ai * HALF + m * 16) * 1024 + col0;
; #pragma unroll
;                 for (int bj = 0; bj < 2; ++bj) {
;                     f32x4 x0, x1;
;                     if (xin_f32) { x0 = *(const f32x4*)(xin_f32 + off + bj * HALF); x1 = *(const f32x4*)(xin_f32 + off + bj * HALF + 4); }
;                     else { const u32x4 w = *(const u32x4*)(xin_b + off + bj * HALF); x0 = (f32x4){bflo(w.x), bfhi(w.x), bflo(w.y), bfhi(w.y)}; x1 = (f32x4){bflo(w.z), bfhi(w.z), bflo(w.w), bfhi(w.w)}; }
;                     x0 = x0 + gv[bj][0] * acc[ai][bj][m][0]; x1 = x1 + gv[bj][1] * acc[ai][bj][m][1];
;                     if (xout_f32) { *(f32x4*)(xout_f32 + off + bj * HALF) = x0; *(f32x4*)(xout_f32 + off + bj * HALF + 4) = x1; }
;                     else { u32x4 w; w.x = cvt_pk_bf16(x0[0], x0[1]); w.y = cvt_pk_bf16(x0[2], x0[3]); w.z = cvt_pk_bf16(x1[0], x1[1]); w.w = cvt_pk_bf16(x1[2], x1[3]); *(u32x4*)(xout_b + off + bj * HALF) = w; }
.LBB0_975:
	v_mov_b32_e32 v146, v206
	s_lshl_b32 s1, s43, 8
	v_readfirstlane_b32 s0, v146
	s_lshr_b32 s22, s0, 1
	s_and_b32 s22, s22, 0x60
	s_or_b32 s1, s22, s1
	v_lshrrev_b32_e32 v0, 1, v146
	s_ashr_i32 s0, s0, 2
	v_and_or_b32 v0, v0, 24, s1
	s_lshl_b32 s1, s42, 8
	s_andn2_b32 s0, s0, 63
	s_add_i32 s22, s0, s1
	s_ashr_i32 s0, s42, 3
	s_mul_hi_i32 s1, s0, 0x6000
	s_mulk_i32 s0, 0x6000
	s_add_u32 s0, s35, s0
	s_addc_u32 s1, s36, s1
	v_lshl_add_u64 v[74:75], v[0:1], 2, s[0:1]
	global_load_dwordx4 v[94:97], v[74:75], off
	global_load_dwordx4 v[90:93], v[74:75], off offset:16
	global_load_dwordx4 v[78:81], v[74:75], off offset:512
	s_nop 0
	global_load_dwordx4 v[74:77], v[74:75], off offset:528
	v_and_or_b32 v174, v146, 15, s22
	v_ashrrev_i32_e32 v175, 31, v174
	v_lshlrev_b64 v[176:177], 10, v[174:175]
	v_or_b32_e32 v176, v176, v0
	v_cndmask_b32_e64 v146, 0, 1, s[16:17]
	v_cmp_ne_u32_e64 s[0:1], 1, v146
	s_andn2_b64 vcc, exec, s[16:17]
	v_lshl_add_u64 v[178:179], v[176:177], 2, s[12:13]
	v_lshl_add_u64 v[208:209], v[176:177], 1, s[2:3]
	v_mov_b32_e32 v210, v178
	v_mov_b32_e32 v211, v179
	s_cmp_lg_u64 s[16:17], 0
	s_cbranch_scc1 .Lmix_epi_f32
	global_load_dwordx4 v[146:149], v[208:209], off
	global_load_dwordx4 v[150:153], v[208:209], off offset:256
	v_add_co_u32_e32 v250, vcc, 0x8000, v208
	v_addc_co_u32_e32 v251, vcc, 0, v209, vcc
	global_load_dwordx4 v[154:157], v[250:251], off
	global_load_dwordx4 v[158:161], v[250:251], off offset:256
	v_add_co_u32_e32 v250, vcc, 0x10000, v208
	v_addc_co_u32_e32 v251, vcc, 0, v209, vcc
	global_load_dwordx4 v[162:165], v[250:251], off
	global_load_dwordx4 v[182:185], v[250:251], off offset:256
	v_add_co_u32_e32 v250, vcc, 0x18000, v208
	v_addc_co_u32_e32 v251, vcc, 0, v209, vcc
	global_load_dwordx4 v[186:189], v[250:251], off
	global_load_dwordx4 v[190:193], v[250:251], off offset:256
	v_add_co_u32_e32 v250, vcc, 0x40000, v208
	v_addc_co_u32_e32 v251, vcc, 0, v209, vcc
	global_load_dwordx4 v[194:197], v[250:251], off
	global_load_dwordx4 v[198:201], v[250:251], off offset:256
	v_add_co_u32_e32 v250, vcc, 0x48000, v208
	v_addc_co_u32_e32 v251, vcc, 0, v209, vcc
	global_load_dwordx4 v[202:205], v[250:251], off
	global_load_dwordx4 v[218:221], v[250:251], off offset:256
	v_add_co_u32_e32 v250, vcc, 0x50000, v208
	v_addc_co_u32_e32 v251, vcc, 0, v209, vcc
	global_load_dwordx4 v[222:225], v[250:251], off
	global_load_dwordx4 v[242:245], v[250:251], off offset:256
	v_add_co_u32_e32 v250, vcc, 0x58000, v208
	v_addc_co_u32_e32 v251, vcc, 0, v209, vcc
	global_load_dwordx4 v[246:249], v[250:251], off
	global_load_dwordx4 v[174:177], v[250:251], off offset:256
	s_waitcnt vmcnt(0)
	v_and_b32_e32 v212, 0xffff0000, v146
	v_lshlrev_b32_e32 v146, 16, v146
	v_fma_f32 v142, v142, v94, v146
	v_fma_f32 v143, v143, v95, v212
	v_and_b32_e32 v212, 0xffff0000, v147
	v_lshlrev_b32_e32 v147, 16, v147
	v_fma_f32 v144, v144, v96, v147
	v_fma_f32 v145, v145, v97, v212
	v_and_b32_e32 v212, 0xffff0000, v148
	v_lshlrev_b32_e32 v148, 16, v148
	v_fma_f32 v138, v138, v90, v148
	v_fma_f32 v139, v139, v91, v212
	v_and_b32_e32 v212, 0xffff0000, v149
	v_lshlrev_b32_e32 v149, 16, v149
	v_fma_f32 v140, v140, v92, v149
	v_fma_f32 v141, v141, v93, v212
	v_cvt_pk_bf16_f32 v142, v142, v143
	v_cvt_pk_bf16_f32 v143, v144, v145
	v_cvt_pk_bf16_f32 v144, v138, v139
	v_cvt_pk_bf16_f32 v145, v140, v141
	v_and_b32_e32 v212, 0xffff0000, v150
	v_lshlrev_b32_e32 v150, 16, v150
	v_fma_f32 v134, v134, v78, v150
	v_fma_f32 v135, v135, v79, v212
	v_and_b32_e32 v212, 0xffff0000, v151
	v_lshlrev_b32_e32 v151, 16, v151
	v_fma_f32 v136, v136, v80, v151
	v_fma_f32 v137, v137, v81, v212
	v_and_b32_e32 v212, 0xffff0000, v152
	v_lshlrev_b32_e32 v152, 16, v152
	v_fma_f32 v130, v130, v74, v152
	v_fma_f32 v131, v131, v75, v212
	v_and_b32_e32 v212, 0xffff0000, v153
	v_lshlrev_b32_e32 v153, 16, v153
	v_fma_f32 v132, v132, v76, v153
	v_fma_f32 v133, v133, v77, v212
	v_cvt_pk_bf16_f32 v134, v134, v135
	v_cvt_pk_bf16_f32 v135, v136, v137
	v_cvt_pk_bf16_f32 v136, v130, v131
	v_cvt_pk_bf16_f32 v137, v132, v133
	global_store_dwordx4 v[208:209], v[142:145], off
	global_store_dwordx4 v[208:209], v[134:137], off offset:256
	v_and_b32_e32 v212, 0xffff0000, v154
	v_lshlrev_b32_e32 v154, 16, v154
	v_fma_f32 v126, v126, v94, v154
	v_fma_f32 v127, v127, v95, v212
	v_and_b32_e32 v212, 0xffff0000, v155
	v_lshlrev_b32_e32 v155, 16, v155
	v_fma_f32 v128, v128, v96, v155
	v_fma_f32 v129, v129, v97, v212
	v_and_b32_e32 v212, 0xffff0000, v156
	v_lshlrev_b32_e32 v156, 16, v156
	v_fma_f32 v122, v122, v90, v156
	v_fma_f32 v123, v123, v91, v212
	v_and_b32_e32 v212, 0xffff0000, v157
	v_lshlrev_b32_e32 v157, 16, v157
	v_fma_f32 v124, v124, v92, v157
	v_fma_f32 v125, v125, v93, v212
	v_cvt_pk_bf16_f32 v126, v126, v127
	v_cvt_pk_bf16_f32 v127, v128, v129
	v_cvt_pk_bf16_f32 v128, v122, v123
	v_cvt_pk_bf16_f32 v129, v124, v125
	v_and_b32_e32 v212, 0xffff0000, v158
	v_lshlrev_b32_e32 v158, 16, v158
	v_fma_f32 v118, v118, v78, v158
	v_fma_f32 v119, v119, v79, v212
	v_and_b32_e32 v212, 0xffff0000, v159
	v_lshlrev_b32_e32 v159, 16, v159
	v_fma_f32 v120, v120, v80, v159
	v_fma_f32 v121, v121, v81, v212
	v_and_b32_e32 v212, 0xffff0000, v160
	v_lshlrev_b32_e32 v160, 16, v160
	v_fma_f32 v114, v114, v74, v160
	v_fma_f32 v115, v115, v75, v212
	v_and_b32_e32 v212, 0xffff0000, v161
	v_lshlrev_b32_e32 v161, 16, v161
	v_fma_f32 v116, v116, v76, v161
	v_fma_f32 v117, v117, v77, v212
	v_cvt_pk_bf16_f32 v118, v118, v119
	v_cvt_pk_bf16_f32 v119, v120, v121
	v_cvt_pk_bf16_f32 v120, v114, v115
	v_cvt_pk_bf16_f32 v121, v116, v117
	v_add_co_u32_e32 v250, vcc, 0x8000, v208
	v_addc_co_u32_e32 v251, vcc, 0, v209, vcc
; __device__ __forceinline__ unsigned cvt_pk_bf16(float lo, float hi) { f32x2_t v = {lo, hi}; bf16x2_t b = __builtin_convertvector(v, bf16x2_t); return __builtin_bit_cast(unsigned, b); }
; __device__ __forceinline__ float bflo(unsigned w) { return __uint_as_float(w << 16); }
; __device__ __forceinline__ float bfhi(unsigned w) { return __uint_as_float(w & 0xffff0000u); }
;     __device__ __forceinline__ void operator()(const f32x4 (&acc)[2][2][4][2], const Unit& u, int wr, int wc, int fr, int fq) const {
;     ...
;             for (int m = 0; m < 4; ++m) { const size_t off = (size_t)(row0 + ai * HALF + m * 16) * 1024 + col0;
; #pragma unroll
;                 for (int bj = 0; bj < 2; ++bj) {
;                     f32x4 x0, x1;
;                     if (xin_f32) { x0 = *(const f32x4*)(xin_f32 + off + bj * HALF); x1 = *(const f32x4*)(xin_f32 + off + bj * HALF + 4); }
;                     else { const u32x4 w = *(const u32x4*)(xin_b + off + bj * HALF); x0 = (f32x4){bflo(w.x), bfhi(w.x), bflo(w.y), bfhi(w.y)}; x1 = (f32x4){bflo(w.z), bfhi(w.z), bflo(w.w), bfhi(w.w)}; }
;                     x0 = x0 + gv[bj][0] * acc[ai][bj][m][0]; x1 = x1 + gv[bj][1] * acc[ai][bj][m][1];
;                     if (xout_f32) { *(f32x4*)(xout_f32 + off + bj * HALF) = x0; *(f32x4*)(xout_f32 + off + bj * HALF + 4) = x1; }
;                     else { u32x4 w; w.x = cvt_pk_bf16(x0[0], x0[1]); w.y = cvt_pk_bf16(x0[2], x0[3]); w.z = cvt_pk_bf16(x1[0], x1[1]); w.w = cvt_pk_bf16(x1[2], x1[3]); *(u32x4*)(xout_b + off + bj * HALF) = w; }
	global_store_dwordx4 v[250:251], v[126:129], off
	global_store_dwordx4 v[250:251], v[118:121], off offset:256
	v_and_b32_e32 v212, 0xffff0000, v162
	v_lshlrev_b32_e32 v162, 16, v162
	v_fma_f32 v110, v110, v94, v162
	v_fma_f32 v111, v111, v95, v212
	v_and_b32_e32 v212, 0xffff0000, v163
	v_lshlrev_b32_e32 v163, 16, v163
	v_fma_f32 v112, v112, v96, v163
	v_fma_f32 v113, v113, v97, v212
	v_and_b32_e32 v212, 0xffff0000, v164
	v_lshlrev_b32_e32 v164, 16, v164
	v_fma_f32 v106, v106, v90, v164
	v_fma_f32 v107, v107, v91, v212
	v_and_b32_e32 v212, 0xffff0000, v165
	v_lshlrev_b32_e32 v165, 16, v165
	v_fma_f32 v108, v108, v92, v165
	v_fma_f32 v109, v109, v93, v212
	v_cvt_pk_bf16_f32 v110, v110, v111
	v_cvt_pk_bf16_f32 v111, v112, v113
	v_cvt_pk_bf16_f32 v112, v106, v107
	v_cvt_pk_bf16_f32 v113, v108, v109
	v_and_b32_e32 v212, 0xffff0000, v182
	v_lshlrev_b32_e32 v182, 16, v182
	v_fma_f32 v102, v102, v78, v182
	v_fma_f32 v103, v103, v79, v212
	v_and_b32_e32 v212, 0xffff0000, v183
	v_lshlrev_b32_e32 v183, 16, v183
	v_fma_f32 v104, v104, v80, v183
	v_fma_f32 v105, v105, v81, v212
	v_and_b32_e32 v212, 0xffff0000, v184
	v_lshlrev_b32_e32 v184, 16, v184
	v_fma_f32 v98, v98, v74, v184
	v_fma_f32 v99, v99, v75, v212
	v_and_b32_e32 v212, 0xffff0000, v185
	v_lshlrev_b32_e32 v185, 16, v185
	v_fma_f32 v100, v100, v76, v185
	v_fma_f32 v101, v101, v77, v212
	v_cvt_pk_bf16_f32 v102, v102, v103
	v_cvt_pk_bf16_f32 v103, v104, v105
	v_cvt_pk_bf16_f32 v104, v98, v99
	v_cvt_pk_bf16_f32 v105, v100, v101
	v_add_co_u32_e32 v250, vcc, 0x10000, v208
	v_addc_co_u32_e32 v251, vcc, 0, v209, vcc
	global_store_dwordx4 v[250:251], v[110:113], off
	global_store_dwordx4 v[250:251], v[102:105], off offset:256
	v_and_b32_e32 v212, 0xffff0000, v186
	v_lshlrev_b32_e32 v186, 16, v186
	v_fma_f32 v86, v86, v94, v186
	v_fma_f32 v87, v87, v95, v212
	v_and_b32_e32 v212, 0xffff0000, v187
	v_lshlrev_b32_e32 v187, 16, v187
	v_fma_f32 v88, v88, v96, v187
	v_fma_f32 v89, v89, v97, v212
	v_and_b32_e32 v212, 0xffff0000, v188
	v_lshlrev_b32_e32 v188, 16, v188
	v_fma_f32 v82, v82, v90, v188
	v_fma_f32 v83, v83, v91, v212
	v_and_b32_e32 v212, 0xffff0000, v189
	v_lshlrev_b32_e32 v189, 16, v189
	v_fma_f32 v84, v84, v92, v189
	v_fma_f32 v85, v85, v93, v212
	v_cvt_pk_bf16_f32 v86, v86, v87
	v_cvt_pk_bf16_f32 v87, v88, v89
	v_cvt_pk_bf16_f32 v88, v82, v83
	v_cvt_pk_bf16_f32 v89, v84, v85
	v_and_b32_e32 v212, 0xffff0000, v190
	v_lshlrev_b32_e32 v190, 16, v190
	v_fma_f32 v70, v70, v78, v190
	v_fma_f32 v71, v71, v79, v212
	v_and_b32_e32 v212, 0xffff0000, v191
	v_lshlrev_b32_e32 v191, 16, v191
	v_fma_f32 v72, v72, v80, v191
	v_fma_f32 v73, v73, v81, v212
	v_and_b32_e32 v212, 0xffff0000, v192
	v_lshlrev_b32_e32 v192, 16, v192
	v_fma_f32 v66, v66, v74, v192
	v_fma_f32 v67, v67, v75, v212
	v_and_b32_e32 v212, 0xffff0000, v193
	v_lshlrev_b32_e32 v193, 16, v193
	v_fma_f32 v68, v68, v76, v193
	v_fma_f32 v69, v69, v77, v212
	v_cvt_pk_bf16_f32 v70, v70, v71
	v_cvt_pk_bf16_f32 v71, v72, v73
	v_cvt_pk_bf16_f32 v72, v66, v67
	v_cvt_pk_bf16_f32 v73, v68, v69
	v_add_co_u32_e32 v250, vcc, 0x18000, v208
	v_addc_co_u32_e32 v251, vcc, 0, v209, vcc
	global_store_dwordx4 v[250:251], v[86:89], off
	global_store_dwordx4 v[250:251], v[70:73], off offset:256
	v_and_b32_e32 v212, 0xffff0000, v194
	v_lshlrev_b32_e32 v194, 16, v194
	v_fma_f32 v62, v62, v94, v194
	v_fma_f32 v63, v63, v95, v212
	v_and_b32_e32 v212, 0xffff0000, v195
	v_lshlrev_b32_e32 v195, 16, v195
	v_fma_f32 v64, v64, v96, v195
	v_fma_f32 v65, v65, v97, v212
	v_and_b32_e32 v212, 0xffff0000, v196
	v_lshlrev_b32_e32 v196, 16, v196
	v_fma_f32 v58, v58, v90, v196
	v_fma_f32 v59, v59, v91, v212
	v_and_b32_e32 v212, 0xffff0000, v197
	v_lshlrev_b32_e32 v197, 16, v197
	v_fma_f32 v60, v60, v92, v197
	v_fma_f32 v61, v61, v93, v212
	v_cvt_pk_bf16_f32 v62, v62, v63
	v_cvt_pk_bf16_f32 v63, v64, v65
	v_cvt_pk_bf16_f32 v64, v58, v59
	v_cvt_pk_bf16_f32 v65, v60, v61
	v_and_b32_e32 v212, 0xffff0000, v198
	v_lshlrev_b32_e32 v198, 16, v198
	v_fma_f32 v54, v54, v78, v198
	v_fma_f32 v55, v55, v79, v212
	v_and_b32_e32 v212, 0xffff0000, v199
	v_lshlrev_b32_e32 v199, 16, v199
	v_fma_f32 v56, v56, v80, v199
	v_fma_f32 v57, v57, v81, v212
	v_and_b32_e32 v212, 0xffff0000, v200
	v_lshlrev_b32_e32 v200, 16, v200
	v_fma_f32 v50, v50, v74, v200
	v_fma_f32 v51, v51, v75, v212
	v_and_b32_e32 v212, 0xffff0000, v201
	v_lshlrev_b32_e32 v201, 16, v201
	v_fma_f32 v52, v52, v76, v201
	v_fma_f32 v53, v53, v77, v212
	v_cvt_pk_bf16_f32 v54, v54, v55
	v_cvt_pk_bf16_f32 v55, v56, v57
	v_cvt_pk_bf16_f32 v56, v50, v51
	v_cvt_pk_bf16_f32 v57, v52, v53
	v_add_co_u32_e32 v250, vcc, 0x40000, v208
	v_addc_co_u32_e32 v251, vcc, 0, v209, vcc
	global_store_dwordx4 v[250:251], v[62:65], off
	global_store_dwordx4 v[250:251], v[54:57], off offset:256
	v_and_b32_e32 v212, 0xffff0000, v202
	v_lshlrev_b32_e32 v202, 16, v202
	v_fma_f32 v46, v46, v94, v202
	v_fma_f32 v47, v47, v95, v212
	v_and_b32_e32 v212, 0xffff0000, v203
	v_lshlrev_b32_e32 v203, 16, v203
	v_fma_f32 v48, v48, v96, v203
	v_fma_f32 v49, v49, v97, v212
	v_and_b32_e32 v212, 0xffff0000, v204
	v_lshlrev_b32_e32 v204, 16, v204
	v_fma_f32 v42, v42, v90, v204
	v_fma_f32 v43, v43, v91, v212
	v_and_b32_e32 v212, 0xffff0000, v205
	v_lshlrev_b32_e32 v205, 16, v205
	v_fma_f32 v44, v44, v92, v205
	v_fma_f32 v45, v45, v93, v212
	v_cvt_pk_bf16_f32 v46, v46, v47
	v_cvt_pk_bf16_f32 v47, v48, v49
	v_cvt_pk_bf16_f32 v48, v42, v43
	v_cvt_pk_bf16_f32 v49, v44, v45
	v_and_b32_e32 v212, 0xffff0000, v218
	v_lshlrev_b32_e32 v218, 16, v218
	v_fma_f32 v38, v38, v78, v218
	v_fma_f32 v39, v39, v79, v212
	v_and_b32_e32 v212, 0xffff0000, v219
	v_lshlrev_b32_e32 v219, 16, v219
; __device__ __forceinline__ unsigned cvt_pk_bf16(float lo, float hi) { f32x2_t v = {lo, hi}; bf16x2_t b = __builtin_convertvector(v, bf16x2_t); return __builtin_bit_cast(unsigned, b); }
; __device__ __forceinline__ float bflo(unsigned w) { return __uint_as_float(w << 16); }
; __device__ __forceinline__ float bfhi(unsigned w) { return __uint_as_float(w & 0xffff0000u); }
;     __device__ __forceinline__ void operator()(const f32x4 (&acc)[2][2][4][2], const Unit& u, int wr, int wc, int fr, int fq) const {
;     ...
;             for (int m = 0; m < 4; ++m) { const size_t off = (size_t)(row0 + ai * HALF + m * 16) * 1024 + col0;
; #pragma unroll
;                 for (int bj = 0; bj < 2; ++bj) {
;                     f32x4 x0, x1;
;                     if (xin_f32) { x0 = *(const f32x4*)(xin_f32 + off + bj * HALF); x1 = *(const f32x4*)(xin_f32 + off + bj * HALF + 4); }
;                     else { const u32x4 w = *(const u32x4*)(xin_b + off + bj * HALF); x0 = (f32x4){bflo(w.x), bfhi(w.x), bflo(w.y), bfhi(w.y)}; x1 = (f32x4){bflo(w.z), bfhi(w.z), bflo(w.w), bfhi(w.w)}; }
;                     x0 = x0 + gv[bj][0] * acc[ai][bj][m][0]; x1 = x1 + gv[bj][1] * acc[ai][bj][m][1];
;                     if (xout_f32) { *(f32x4*)(xout_f32 + off + bj * HALF) = x0; *(f32x4*)(xout_f32 + off + bj * HALF + 4) = x1; }
;                     else { u32x4 w; w.x = cvt_pk_bf16(x0[0], x0[1]); w.y = cvt_pk_bf16(x0[2], x0[3]); w.z = cvt_pk_bf16(x1[0], x1[1]); w.w = cvt_pk_bf16(x1[2], x1[3]); *(u32x4*)(xout_b + off + bj * HALF) = w; }
	v_fma_f32 v40, v40, v80, v219
	v_fma_f32 v41, v41, v81, v212
	v_and_b32_e32 v212, 0xffff0000, v220
	v_lshlrev_b32_e32 v220, 16, v220
	v_fma_f32 v34, v34, v74, v220
	v_fma_f32 v35, v35, v75, v212
	v_and_b32_e32 v212, 0xffff0000, v221
	v_lshlrev_b32_e32 v221, 16, v221
	v_fma_f32 v36, v36, v76, v221
	v_fma_f32 v37, v37, v77, v212
	v_cvt_pk_bf16_f32 v38, v38, v39
	v_cvt_pk_bf16_f32 v39, v40, v41
	v_cvt_pk_bf16_f32 v40, v34, v35
	v_cvt_pk_bf16_f32 v41, v36, v37
	v_add_co_u32_e32 v250, vcc, 0x48000, v208
	v_addc_co_u32_e32 v251, vcc, 0, v209, vcc
	global_store_dwordx4 v[250:251], v[46:49], off
	global_store_dwordx4 v[250:251], v[38:41], off offset:256
	v_and_b32_e32 v212, 0xffff0000, v222
	v_lshlrev_b32_e32 v222, 16, v222
	v_fma_f32 v30, v30, v94, v222
	v_fma_f32 v31, v31, v95, v212
	v_and_b32_e32 v212, 0xffff0000, v223
	v_lshlrev_b32_e32 v223, 16, v223
	v_fma_f32 v32, v32, v96, v223
	v_fma_f32 v33, v33, v97, v212
	v_and_b32_e32 v212, 0xffff0000, v224
	v_lshlrev_b32_e32 v224, 16, v224
	v_fma_f32 v26, v26, v90, v224
	v_fma_f32 v27, v27, v91, v212
	v_and_b32_e32 v212, 0xffff0000, v225
	v_lshlrev_b32_e32 v225, 16, v225
	v_fma_f32 v28, v28, v92, v225
	v_fma_f32 v29, v29, v93, v212
	v_cvt_pk_bf16_f32 v30, v30, v31
	v_cvt_pk_bf16_f32 v31, v32, v33
	v_cvt_pk_bf16_f32 v32, v26, v27
	v_cvt_pk_bf16_f32 v33, v28, v29
	v_and_b32_e32 v212, 0xffff0000, v242
	v_lshlrev_b32_e32 v242, 16, v242
	v_fma_f32 v22, v22, v78, v242
	v_fma_f32 v23, v23, v79, v212
	v_and_b32_e32 v212, 0xffff0000, v243
	v_lshlrev_b32_e32 v243, 16, v243
	v_fma_f32 v24, v24, v80, v243
	v_fma_f32 v25, v25, v81, v212
	v_and_b32_e32 v212, 0xffff0000, v244
	v_lshlrev_b32_e32 v244, 16, v244
	v_fma_f32 v18, v18, v74, v244
	v_fma_f32 v19, v19, v75, v212
	v_and_b32_e32 v212, 0xffff0000, v245
	v_lshlrev_b32_e32 v245, 16, v245
	v_fma_f32 v20, v20, v76, v245
	v_fma_f32 v21, v21, v77, v212
	v_cvt_pk_bf16_f32 v22, v22, v23
	v_cvt_pk_bf16_f32 v23, v24, v25
	v_cvt_pk_bf16_f32 v24, v18, v19
	v_cvt_pk_bf16_f32 v25, v20, v21
	v_add_co_u32_e32 v250, vcc, 0x50000, v208
	v_addc_co_u32_e32 v251, vcc, 0, v209, vcc
	global_store_dwordx4 v[250:251], v[30:33], off
	global_store_dwordx4 v[250:251], v[22:25], off offset:256
	v_and_b32_e32 v212, 0xffff0000, v246
	v_lshlrev_b32_e32 v246, 16, v246
	v_fma_f32 v14, v14, v94, v246
	v_fma_f32 v15, v15, v95, v212
	v_and_b32_e32 v212, 0xffff0000, v247
	v_lshlrev_b32_e32 v247, 16, v247
	v_fma_f32 v16, v16, v96, v247
	v_fma_f32 v17, v17, v97, v212
	v_and_b32_e32 v212, 0xffff0000, v248
	v_lshlrev_b32_e32 v248, 16, v248
	v_fma_f32 v10, v10, v90, v248
	v_fma_f32 v11, v11, v91, v212
	v_and_b32_e32 v212, 0xffff0000, v249
	v_lshlrev_b32_e32 v249, 16, v249
	v_fma_f32 v12, v12, v92, v249
	v_fma_f32 v13, v13, v93, v212
	v_cvt_pk_bf16_f32 v14, v14, v15
	v_cvt_pk_bf16_f32 v15, v16, v17
	v_cvt_pk_bf16_f32 v16, v10, v11
	v_cvt_pk_bf16_f32 v17, v12, v13
	v_and_b32_e32 v212, 0xffff0000, v174
	v_lshlrev_b32_e32 v174, 16, v174
	v_fma_f32 v6, v6, v78, v174
	v_fma_f32 v7, v7, v79, v212
	v_and_b32_e32 v212, 0xffff0000, v175
	v_lshlrev_b32_e32 v175, 16, v175
	v_fma_f32 v8, v8, v80, v175
	v_fma_f32 v9, v9, v81, v212
	v_and_b32_e32 v212, 0xffff0000, v176
	v_lshlrev_b32_e32 v176, 16, v176
	v_fma_f32 v2, v2, v74, v176
	v_fma_f32 v3, v3, v75, v212
	v_and_b32_e32 v212, 0xffff0000, v177
	v_lshlrev_b32_e32 v177, 16, v177
	v_fma_f32 v4, v4, v76, v177
	v_fma_f32 v5, v5, v77, v212
	v_cvt_pk_bf16_f32 v6, v6, v7
	v_cvt_pk_bf16_f32 v7, v8, v9
	v_cvt_pk_bf16_f32 v8, v2, v3
	v_cvt_pk_bf16_f32 v9, v4, v5
	v_add_co_u32_e32 v250, vcc, 0x58000, v208
	v_addc_co_u32_e32 v251, vcc, 0, v209, vcc
	global_store_dwordx4 v[250:251], v[14:17], off
	global_store_dwordx4 v[250:251], v[6:9], off offset:256
	s_branch .Lmix_epi_done
.Lmix_epi_f32:
	global_load_dwordx4 v[146:149], v[210:211], off
	global_load_dwordx4 v[150:153], v[210:211], off offset:16
	global_load_dwordx4 v[154:157], v[210:211], off offset:512
	global_load_dwordx4 v[158:161], v[210:211], off offset:528
	v_add_co_u32_e32 v250, vcc, 0x10000, v210
	v_addc_co_u32_e32 v251, vcc, 0, v211, vcc
	global_load_dwordx4 v[162:165], v[250:251], off
	global_load_dwordx4 v[182:185], v[250:251], off offset:16
	global_load_dwordx4 v[186:189], v[250:251], off offset:512
	global_load_dwordx4 v[190:193], v[250:251], off offset:528
	v_add_co_u32_e32 v250, vcc, 0x20000, v210
	v_addc_co_u32_e32 v251, vcc, 0, v211, vcc
	global_load_dwordx4 v[194:197], v[250:251], off
	global_load_dwordx4 v[198:201], v[250:251], off offset:16
	global_load_dwordx4 v[202:205], v[250:251], off offset:512
	global_load_dwordx4 v[218:221], v[250:251], off offset:528
	v_add_co_u32_e32 v250, vcc, 0x30000, v210
	v_addc_co_u32_e32 v251, vcc, 0, v211, vcc
	global_load_dwordx4 v[222:225], v[250:251], off
	global_load_dwordx4 v[242:245], v[250:251], off offset:16
	global_load_dwordx4 v[246:249], v[250:251], off offset:512
	global_load_dwordx4 v[174:177], v[250:251], off offset:528
	s_waitcnt vmcnt(0)
; __device__ __forceinline__ unsigned cvt_pk_bf16(float lo, float hi) { f32x2_t v = {lo, hi}; bf16x2_t b = __builtin_convertvector(v, bf16x2_t); return __builtin_bit_cast(unsigned, b); }
; __device__ __forceinline__ float bflo(unsigned w) { return __uint_as_float(w << 16); }
; __device__ __forceinline__ float bfhi(unsigned w) { return __uint_as_float(w & 0xffff0000u); }
;     __device__ __forceinline__ void operator()(const f32x4 (&acc)[2][2][4][2], const Unit& u, int wr, int wc, int fr, int fq) const {
;     ...
;             for (int m = 0; m < 4; ++m) { const size_t off = (size_t)(row0 + ai * HALF + m * 16) * 1024 + col0;
; #pragma unroll
;                 for (int bj = 0; bj < 2; ++bj) {
;                     f32x4 x0, x1;
;                     if (xin_f32) { x0 = *(const f32x4*)(xin_f32 + off + bj * HALF); x1 = *(const f32x4*)(xin_f32 + off + bj * HALF + 4); }
;                     else { const u32x4 w = *(const u32x4*)(xin_b + off + bj * HALF); x0 = (f32x4){bflo(w.x), bfhi(w.x), bflo(w.y), bfhi(w.y)}; x1 = (f32x4){bflo(w.z), bfhi(w.z), bflo(w.w), bfhi(w.w)}; }
;                     x0 = x0 + gv[bj][0] * acc[ai][bj][m][0]; x1 = x1 + gv[bj][1] * acc[ai][bj][m][1];
;                     if (xout_f32) { *(f32x4*)(xout_f32 + off + bj * HALF) = x0; *(f32x4*)(xout_f32 + off + bj * HALF + 4) = x1; }
;                     else { u32x4 w; w.x = cvt_pk_bf16(x0[0], x0[1]); w.y = cvt_pk_bf16(x0[2], x0[3]); w.z = cvt_pk_bf16(x1[0], x1[1]); w.w = cvt_pk_bf16(x1[2], x1[3]); *(u32x4*)(xout_b + off + bj * HALF) = w; }
	v_fma_f32 v142, v142, v94, v146
	v_fma_f32 v143, v143, v95, v147
	v_fma_f32 v144, v144, v96, v148
	v_fma_f32 v145, v145, v97, v149
	v_fma_f32 v138, v138, v90, v150
	v_fma_f32 v139, v139, v91, v151
	v_fma_f32 v140, v140, v92, v152
	v_fma_f32 v141, v141, v93, v153
	v_cvt_pk_bf16_f32 v142, v142, v143
	v_cvt_pk_bf16_f32 v143, v144, v145
	v_cvt_pk_bf16_f32 v144, v138, v139
	v_cvt_pk_bf16_f32 v145, v140, v141
	v_fma_f32 v134, v134, v78, v154
	v_fma_f32 v135, v135, v79, v155
	v_fma_f32 v136, v136, v80, v156
	v_fma_f32 v137, v137, v81, v157
	v_fma_f32 v130, v130, v74, v158
	v_fma_f32 v131, v131, v75, v159
	v_fma_f32 v132, v132, v76, v160
	v_fma_f32 v133, v133, v77, v161
	v_cvt_pk_bf16_f32 v134, v134, v135
	v_cvt_pk_bf16_f32 v135, v136, v137
	v_cvt_pk_bf16_f32 v136, v130, v131
	v_cvt_pk_bf16_f32 v137, v132, v133
	global_store_dwordx4 v[208:209], v[142:145], off
	global_store_dwordx4 v[208:209], v[134:137], off offset:256
	v_fma_f32 v126, v126, v94, v162
	v_fma_f32 v127, v127, v95, v163
	v_fma_f32 v128, v128, v96, v164
	v_fma_f32 v129, v129, v97, v165
	v_fma_f32 v122, v122, v90, v182
	v_fma_f32 v123, v123, v91, v183
	v_fma_f32 v124, v124, v92, v184
	v_fma_f32 v125, v125, v93, v185
	v_cvt_pk_bf16_f32 v126, v126, v127
	v_cvt_pk_bf16_f32 v127, v128, v129
	v_cvt_pk_bf16_f32 v128, v122, v123
	v_cvt_pk_bf16_f32 v129, v124, v125
	v_fma_f32 v118, v118, v78, v186
	v_fma_f32 v119, v119, v79, v187
	v_fma_f32 v120, v120, v80, v188
	v_fma_f32 v121, v121, v81, v189
	v_fma_f32 v114, v114, v74, v190
	v_fma_f32 v115, v115, v75, v191
	v_fma_f32 v116, v116, v76, v192
	v_fma_f32 v117, v117, v77, v193
	v_cvt_pk_bf16_f32 v118, v118, v119
	v_cvt_pk_bf16_f32 v119, v120, v121
	v_cvt_pk_bf16_f32 v120, v114, v115
	v_cvt_pk_bf16_f32 v121, v116, v117
	v_add_co_u32_e32 v250, vcc, 0x8000, v208
	v_addc_co_u32_e32 v251, vcc, 0, v209, vcc
	global_store_dwordx4 v[250:251], v[126:129], off
	global_store_dwordx4 v[250:251], v[118:121], off offset:256
	v_fma_f32 v110, v110, v94, v194
	v_fma_f32 v111, v111, v95, v195
	v_fma_f32 v112, v112, v96, v196
	v_fma_f32 v113, v113, v97, v197
	v_fma_f32 v106, v106, v90, v198
	v_fma_f32 v107, v107, v91, v199
	v_fma_f32 v108, v108, v92, v200
	v_fma_f32 v109, v109, v93, v201
	v_cvt_pk_bf16_f32 v110, v110, v111
	v_cvt_pk_bf16_f32 v111, v112, v113
	v_cvt_pk_bf16_f32 v112, v106, v107
	v_cvt_pk_bf16_f32 v113, v108, v109
	v_fma_f32 v102, v102, v78, v202
	v_fma_f32 v103, v103, v79, v203
	v_fma_f32 v104, v104, v80, v204
	v_fma_f32 v105, v105, v81, v205
	v_fma_f32 v98, v98, v74, v218
	v_fma_f32 v99, v99, v75, v219
	v_fma_f32 v100, v100, v76, v220
	v_fma_f32 v101, v101, v77, v221
	v_cvt_pk_bf16_f32 v102, v102, v103
	v_cvt_pk_bf16_f32 v103, v104, v105
	v_cvt_pk_bf16_f32 v104, v98, v99
	v_cvt_pk_bf16_f32 v105, v100, v101
	v_add_co_u32_e32 v250, vcc, 0x10000, v208
	v_addc_co_u32_e32 v251, vcc, 0, v209, vcc
	global_store_dwordx4 v[250:251], v[110:113], off
	global_store_dwordx4 v[250:251], v[102:105], off offset:256
	v_fma_f32 v86, v86, v94, v222
	v_fma_f32 v87, v87, v95, v223
	v_fma_f32 v88, v88, v96, v224
	v_fma_f32 v89, v89, v97, v225
	v_fma_f32 v82, v82, v90, v242
	v_fma_f32 v83, v83, v91, v243
	v_fma_f32 v84, v84, v92, v244
	v_fma_f32 v85, v85, v93, v245
	v_cvt_pk_bf16_f32 v86, v86, v87
	v_cvt_pk_bf16_f32 v87, v88, v89
	v_cvt_pk_bf16_f32 v88, v82, v83
	v_cvt_pk_bf16_f32 v89, v84, v85
	v_fma_f32 v70, v70, v78, v246
	v_fma_f32 v71, v71, v79, v247
	v_fma_f32 v72, v72, v80, v248
	v_fma_f32 v73, v73, v81, v249
	v_fma_f32 v66, v66, v74, v174
	v_fma_f32 v67, v67, v75, v175
	v_fma_f32 v68, v68, v76, v176
	v_fma_f32 v69, v69, v77, v177
	v_cvt_pk_bf16_f32 v70, v70, v71
	v_cvt_pk_bf16_f32 v71, v72, v73
	v_cvt_pk_bf16_f32 v72, v66, v67
	v_cvt_pk_bf16_f32 v73, v68, v69
	v_add_co_u32_e32 v250, vcc, 0x18000, v208
	v_addc_co_u32_e32 v251, vcc, 0, v209, vcc
	global_store_dwordx4 v[250:251], v[86:89], off
	global_store_dwordx4 v[250:251], v[70:73], off offset:256
	v_add_co_u32_e32 v250, vcc, 0x80000, v210
	v_addc_co_u32_e32 v251, vcc, 0, v211, vcc
	global_load_dwordx4 v[146:149], v[250:251], off
	global_load_dwordx4 v[150:153], v[250:251], off offset:16
	global_load_dwordx4 v[154:157], v[250:251], off offset:512
	global_load_dwordx4 v[158:161], v[250:251], off offset:528
	v_add_co_u32_e32 v250, vcc, 0x90000, v210
	v_addc_co_u32_e32 v251, vcc, 0, v211, vcc
	global_load_dwordx4 v[162:165], v[250:251], off
	global_load_dwordx4 v[182:185], v[250:251], off offset:16
	global_load_dwordx4 v[186:189], v[250:251], off offset:512
	global_load_dwordx4 v[190:193], v[250:251], off offset:528
	v_add_co_u32_e32 v250, vcc, 0xa0000, v210
	v_addc_co_u32_e32 v251, vcc, 0, v211, vcc
	global_load_dwordx4 v[194:197], v[250:251], off
	global_load_dwordx4 v[198:201], v[250:251], off offset:16
	global_load_dwordx4 v[202:205], v[250:251], off offset:512
	global_load_dwordx4 v[218:221], v[250:251], off offset:528
	v_add_co_u32_e32 v250, vcc, 0xb0000, v210
	v_addc_co_u32_e32 v251, vcc, 0, v211, vcc
	global_load_dwordx4 v[222:225], v[250:251], off
	global_load_dwordx4 v[242:245], v[250:251], off offset:16
	global_load_dwordx4 v[246:249], v[250:251], off offset:512
	global_load_dwordx4 v[174:177], v[250:251], off offset:528
	s_waitcnt vmcnt(0)
; __device__ __forceinline__ unsigned cvt_pk_bf16(float lo, float hi) { f32x2_t v = {lo, hi}; bf16x2_t b = __builtin_convertvector(v, bf16x2_t); return __builtin_bit_cast(unsigned, b); }
; #define PG8_BAR __builtin_amdgcn_s_barrier()
;     __device__ __forceinline__ void operator()(const f32x4 (&acc)[2][2][4][2], const Unit& u, int wr, int wc, int fr, int fq) const {
;     ...
;                     x0 = x0 + gv[bj][0] * acc[ai][bj][m][0]; x1 = x1 + gv[bj][1] * acc[ai][bj][m][1];
;                     if (xout_f32) { *(f32x4*)(xout_f32 + off + bj * HALF) = x0; *(f32x4*)(xout_f32 + off + bj * HALF + 4) = x1; }
;                     else { u32x4 w; w.x = cvt_pk_bf16(x0[0], x0[1]); w.y = cvt_pk_bf16(x0[2], x0[3]); w.z = cvt_pk_bf16(x1[0], x1[1]); w.w = cvt_pk_bf16(x1[2], x1[3]); *(u32x4*)(xout_b + off + bj * HALF) = w; }
; template <class Epi, class Sched>
; __device__ __forceinline__ void gemm_phase(LAS unsigned char* lds, Gemm g, Sched S, const Epi& E) {
;     ...
;         if (!has_next) break;
; #pragma unroll
;         for (int a = 0; a < 2; ++a)
; #pragma unroll
;             for (int b = 0; b < 2; ++b)
; #pragma unroll
;                 for (int m = 0; m < 4; ++m)
; #pragma unroll
;                     for (int n = 0; n < 2; ++n) acc[a][b][m][n] = (f32x4){0.f, 0.f, 0.f, 0.f};
;         cur = nxt; cA = nA; cB = nB; ++ui;
;         if (wr == 1) PG8_BAR;
	v_fma_f32 v62, v62, v94, v146
	v_fma_f32 v63, v63, v95, v147
	v_fma_f32 v64, v64, v96, v148
	v_fma_f32 v65, v65, v97, v149
	v_fma_f32 v58, v58, v90, v150
	v_fma_f32 v59, v59, v91, v151
	v_fma_f32 v60, v60, v92, v152
	v_fma_f32 v61, v61, v93, v153
	v_cvt_pk_bf16_f32 v62, v62, v63
	v_cvt_pk_bf16_f32 v63, v64, v65
	v_cvt_pk_bf16_f32 v64, v58, v59
	v_cvt_pk_bf16_f32 v65, v60, v61
	v_fma_f32 v54, v54, v78, v154
	v_fma_f32 v55, v55, v79, v155
	v_fma_f32 v56, v56, v80, v156
	v_fma_f32 v57, v57, v81, v157
	v_fma_f32 v50, v50, v74, v158
	v_fma_f32 v51, v51, v75, v159
	v_fma_f32 v52, v52, v76, v160
	v_fma_f32 v53, v53, v77, v161
	v_cvt_pk_bf16_f32 v54, v54, v55
	v_cvt_pk_bf16_f32 v55, v56, v57
	v_cvt_pk_bf16_f32 v56, v50, v51
	v_cvt_pk_bf16_f32 v57, v52, v53
	v_add_co_u32_e32 v250, vcc, 0x40000, v208
	v_addc_co_u32_e32 v251, vcc, 0, v209, vcc
	global_store_dwordx4 v[250:251], v[62:65], off
	global_store_dwordx4 v[250:251], v[54:57], off offset:256
	v_fma_f32 v46, v46, v94, v162
	v_fma_f32 v47, v47, v95, v163
	v_fma_f32 v48, v48, v96, v164
	v_fma_f32 v49, v49, v97, v165
	v_fma_f32 v42, v42, v90, v182
	v_fma_f32 v43, v43, v91, v183
	v_fma_f32 v44, v44, v92, v184
	v_fma_f32 v45, v45, v93, v185
	v_cvt_pk_bf16_f32 v46, v46, v47
	v_cvt_pk_bf16_f32 v47, v48, v49
	v_cvt_pk_bf16_f32 v48, v42, v43
	v_cvt_pk_bf16_f32 v49, v44, v45
	v_fma_f32 v38, v38, v78, v186
	v_fma_f32 v39, v39, v79, v187
	v_fma_f32 v40, v40, v80, v188
	v_fma_f32 v41, v41, v81, v189
	v_fma_f32 v34, v34, v74, v190
	v_fma_f32 v35, v35, v75, v191
	v_fma_f32 v36, v36, v76, v192
	v_fma_f32 v37, v37, v77, v193
	v_cvt_pk_bf16_f32 v38, v38, v39
	v_cvt_pk_bf16_f32 v39, v40, v41
	v_cvt_pk_bf16_f32 v40, v34, v35
	v_cvt_pk_bf16_f32 v41, v36, v37
	v_add_co_u32_e32 v250, vcc, 0x48000, v208
	v_addc_co_u32_e32 v251, vcc, 0, v209, vcc
	global_store_dwordx4 v[250:251], v[46:49], off
	global_store_dwordx4 v[250:251], v[38:41], off offset:256
	v_fma_f32 v30, v30, v94, v194
	v_fma_f32 v31, v31, v95, v195
	v_fma_f32 v32, v32, v96, v196
	v_fma_f32 v33, v33, v97, v197
	v_fma_f32 v26, v26, v90, v198
	v_fma_f32 v27, v27, v91, v199
	v_fma_f32 v28, v28, v92, v200
	v_fma_f32 v29, v29, v93, v201
	v_cvt_pk_bf16_f32 v30, v30, v31
	v_cvt_pk_bf16_f32 v31, v32, v33
	v_cvt_pk_bf16_f32 v32, v26, v27
	v_cvt_pk_bf16_f32 v33, v28, v29
	v_fma_f32 v22, v22, v78, v202
	v_fma_f32 v23, v23, v79, v203
	v_fma_f32 v24, v24, v80, v204
	v_fma_f32 v25, v25, v81, v205
	v_fma_f32 v18, v18, v74, v218
	v_fma_f32 v19, v19, v75, v219
	v_fma_f32 v20, v20, v76, v220
	v_fma_f32 v21, v21, v77, v221
	v_cvt_pk_bf16_f32 v22, v22, v23
	v_cvt_pk_bf16_f32 v23, v24, v25
	v_cvt_pk_bf16_f32 v24, v18, v19
	v_cvt_pk_bf16_f32 v25, v20, v21
	v_add_co_u32_e32 v250, vcc, 0x50000, v208
	v_addc_co_u32_e32 v251, vcc, 0, v209, vcc
	global_store_dwordx4 v[250:251], v[30:33], off
	global_store_dwordx4 v[250:251], v[22:25], off offset:256
	v_fma_f32 v14, v14, v94, v222
	v_fma_f32 v15, v15, v95, v223
	v_fma_f32 v16, v16, v96, v224
	v_fma_f32 v17, v17, v97, v225
	v_fma_f32 v10, v10, v90, v242
	v_fma_f32 v11, v11, v91, v243
	v_fma_f32 v12, v12, v92, v244
	v_fma_f32 v13, v13, v93, v245
	v_cvt_pk_bf16_f32 v14, v14, v15
	v_cvt_pk_bf16_f32 v15, v16, v17
	v_cvt_pk_bf16_f32 v16, v10, v11
	v_cvt_pk_bf16_f32 v17, v12, v13
	v_fma_f32 v6, v6, v78, v246
	v_fma_f32 v7, v7, v79, v247
	v_fma_f32 v8, v8, v80, v248
	v_fma_f32 v9, v9, v81, v249
	v_fma_f32 v2, v2, v74, v174
	v_fma_f32 v3, v3, v75, v175
	v_fma_f32 v4, v4, v76, v176
	v_fma_f32 v5, v5, v77, v177
	v_cvt_pk_bf16_f32 v6, v6, v7
	v_cvt_pk_bf16_f32 v7, v8, v9
	v_cvt_pk_bf16_f32 v8, v2, v3
	v_cvt_pk_bf16_f32 v9, v4, v5
	v_add_co_u32_e32 v250, vcc, 0x58000, v208
	v_addc_co_u32_e32 v251, vcc, 0, v209, vcc
	global_store_dwordx4 v[250:251], v[14:17], off
	global_store_dwordx4 v[250:251], v[6:9], off offset:256
.Lmix_epi_done:
	s_andn2_b64 vcc, exec, s[20:21]
	s_mov_b64 s[0:1], -1
	s_cbranch_vccnz .LBB0_970
	s_andn2_b64 vcc, exec, s[10:11]
	s_cbranch_vccnz .LBB0_969
	s_barrier
	s_branch .LBB0_969

; __device__ __forceinline__ unsigned cvt_pk_bf16(float lo, float hi) { f32x2_t v = {lo, hi}; bf16x2_t b = __builtin_convertvector(v, bf16x2_t); return __builtin_bit_cast(unsigned, b); }
; __device__ __forceinline__ float bflo(unsigned w) { return __uint_as_float(w << 16); }
; __device__ __forceinline__ float bfhi(unsigned w) { return __uint_as_float(w & 0xffff0000u); }
;     __device__ __forceinline__ void operator()(const f32x4 (&acc)[2][2][4][2], const Unit& u, int wr, int wc, int fr, int fq) const {
;         const int col0 = u.pn * BM + wc * 32 + 8 * fq; const int row0 = u.pm * BM + wr * 64 + fr;
;         const float* gp = gate + (size_t)(u.pm >> 3) * 6144 + col0;
;         f32x4 gv[2][2];
; #pragma unroll
;         for (int bj = 0; bj < 2; ++bj)
; #pragma unroll
;             for (int n = 0; n < 2; ++n) gv[bj][n] = *(const f32x4*)(gp + bj * HALF + n * 4);
; #pragma unroll
;         for (int ai = 0; ai < 2; ++ai)
; #pragma unroll
;             for (int m = 0; m < 4; ++m) { const size_t off = (size_t)(row0 + ai * HALF + m * 16) * 1024 + col0;
; #pragma unroll
;                 for (int bj = 0; bj < 2; ++bj) {
;                     f32x4 x0, x1;
;                     if (xin_f32) { x0 = *(const f32x4*)(xin_f32 + off + bj * HALF); x1 = *(const f32x4*)(xin_f32 + off + bj * HALF + 4); }
;                     else { const u32x4 w = *(const u32x4*)(xin_b + off + bj * HALF); x0 = (f32x4){bflo(w.x), bfhi(w.x), bflo(w.y), bfhi(w.y)}; x1 = (f32x4){bflo(w.z), bfhi(w.z), bflo(w.w), bfhi(w.w)}; }
;                     x0 = x0 + gv[bj][0] * acc[ai][bj][m][0]; x1 = x1 + gv[bj][1] * acc[ai][bj][m][1];
;                     if (xout_f32) { *(f32x4*)(xout_f32 + off + bj * HALF) = x0; *(f32x4*)(xout_f32 + off + bj * HALF + 4) = x1; }
;                     else { u32x4 w; w.x = cvt_pk_bf16(x0[0], x0[1]); w.y = cvt_pk_bf16(x0[2], x0[3]); w.z = cvt_pk_bf16(x1[0], x1[1]); w.w = cvt_pk_bf16(x1[2], x1[3]); *(u32x4*)(xout_b + off + bj * HALF) = w; }
.LBB0_1183:
	v_mov_b32_e32 v82, v206
	s_lshl_b32 s19, s26, 8
	v_readfirstlane_b32 s5, v82
	s_lshr_b32 s21, s5, 1
	s_and_b32 s21, s21, 0x60
	s_or_b32 s19, s21, s19
	v_lshrrev_b32_e32 v83, 1, v82
	s_ashr_i32 s5, s5, 2
	v_and_or_b32 v152, v83, 24, s19
	s_lshl_b32 s19, s4, 8
	s_andn2_b32 s5, s5, 63
	s_add_i32 s5, s5, s19
	v_and_or_b32 v166, v82, 15, s5
	v_ashrrev_i32_e32 v167, 31, v166
	v_ashrrev_i32_e32 v153, 31, v152
	v_lshlrev_b64 v[82:83], 10, v[166:167]
	v_lshl_add_u64 v[158:159], v[82:83], 0, v[152:153]
	s_ashr_i32 s4, s4, 3
	v_lshl_add_u64 v[168:169], v[158:159], 1, s[2:3]
	s_mul_hi_i32 s5, s4, 0x6000
	s_mulk_i32 s4, 0x6000
	s_add_u32 s4, s46, s4
	s_addc_u32 s5, s47, s5
	v_lshl_add_u64 v[82:83], v[152:153], 2, s[4:5]
	global_load_dwordx4 v[102:105], v[82:83], off
	global_load_dwordx4 v[98:101], v[82:83], off offset:16
	global_load_dwordx4 v[86:89], v[82:83], off offset:512
	s_nop 0
	global_load_dwordx4 v[82:85], v[82:83], off offset:528
	v_cndmask_b32_e64 v160, 0, 1, s[16:17]
	v_cmp_ne_u32_e64 s[4:5], 1, v160
	s_andn2_b64 vcc, exec, s[16:17]
	v_lshl_add_u64 v[170:171], v[158:159], 2, s[12:13]
	v_mov_b32_e32 v208, v168
	v_mov_b32_e32 v209, v169
	v_mov_b32_e32 v210, v170
	v_mov_b32_e32 v211, v171
	global_load_dwordx4 v[152:155], v[208:209], off
	global_load_dwordx4 v[156:159], v[208:209], off offset:256
	v_add_co_u32_e32 v250, vcc, 0x8000, v208
	v_addc_co_u32_e32 v251, vcc, 0, v209, vcc
	global_load_dwordx4 v[160:163], v[250:251], off
	global_load_dwordx4 v[164:167], v[250:251], off offset:256
	v_add_co_u32_e32 v250, vcc, 0x10000, v208
	v_addc_co_u32_e32 v251, vcc, 0, v209, vcc
	global_load_dwordx4 v[168:171], v[250:251], off
	global_load_dwordx4 v[174:177], v[250:251], off offset:256
	v_add_co_u32_e32 v250, vcc, 0x18000, v208
	v_addc_co_u32_e32 v251, vcc, 0, v209, vcc
	global_load_dwordx4 v[178:181], v[250:251], off
	global_load_dwordx4 v[182:185], v[250:251], off offset:256
	v_add_co_u32_e32 v250, vcc, 0x40000, v208
	v_addc_co_u32_e32 v251, vcc, 0, v209, vcc
	global_load_dwordx4 v[186:189], v[250:251], off
	global_load_dwordx4 v[190:193], v[250:251], off offset:256
	v_add_co_u32_e32 v250, vcc, 0x48000, v208
	v_addc_co_u32_e32 v251, vcc, 0, v209, vcc
	global_load_dwordx4 v[194:197], v[250:251], off
	global_load_dwordx4 v[198:201], v[250:251], off offset:256
	v_add_co_u32_e32 v250, vcc, 0x50000, v208
	v_addc_co_u32_e32 v251, vcc, 0, v209, vcc
	global_load_dwordx4 v[218:221], v[250:251], off
	global_load_dwordx4 v[222:225], v[250:251], off offset:256
	v_add_co_u32_e32 v250, vcc, 0x58000, v208
	v_addc_co_u32_e32 v251, vcc, 0, v209, vcc
	global_load_dwordx4 v[242:245], v[250:251], off
	global_load_dwordx4 v[246:249], v[250:251], off offset:256
	s_cmp_lg_u64 s[16:17], 0
	s_waitcnt vmcnt(0)
	s_cbranch_scc1 .Ldown_epi_f32
	v_and_b32_e32 v212, 0xffff0000, v152
	v_lshlrev_b32_e32 v152, 16, v152
	v_fma_f32 v142, v142, v102, v152
	v_fma_f32 v143, v143, v103, v212
	v_and_b32_e32 v212, 0xffff0000, v153
	v_lshlrev_b32_e32 v153, 16, v153
	v_fma_f32 v144, v144, v104, v153
	v_fma_f32 v145, v145, v105, v212
	v_and_b32_e32 v212, 0xffff0000, v154
	v_lshlrev_b32_e32 v154, 16, v154
	v_fma_f32 v138, v138, v98, v154
	v_fma_f32 v139, v139, v99, v212
	v_and_b32_e32 v212, 0xffff0000, v155
	v_lshlrev_b32_e32 v155, 16, v155
	v_fma_f32 v140, v140, v100, v155
	v_fma_f32 v141, v141, v101, v212
	v_cvt_pk_bf16_f32 v142, v142, v143
	v_cvt_pk_bf16_f32 v143, v144, v145
	v_cvt_pk_bf16_f32 v144, v138, v139
	v_cvt_pk_bf16_f32 v145, v140, v141
	v_and_b32_e32 v212, 0xffff0000, v156
	v_lshlrev_b32_e32 v156, 16, v156
	v_fma_f32 v134, v134, v86, v156
	v_fma_f32 v135, v135, v87, v212
	v_and_b32_e32 v212, 0xffff0000, v157
	v_lshlrev_b32_e32 v157, 16, v157
	v_fma_f32 v136, v136, v88, v157
	v_fma_f32 v137, v137, v89, v212
	v_and_b32_e32 v212, 0xffff0000, v158
	v_lshlrev_b32_e32 v158, 16, v158
	v_fma_f32 v130, v130, v82, v158
	v_fma_f32 v131, v131, v83, v212
	v_and_b32_e32 v212, 0xffff0000, v159
	v_lshlrev_b32_e32 v159, 16, v159
	v_fma_f32 v132, v132, v84, v159
	v_fma_f32 v133, v133, v85, v212
	v_cvt_pk_bf16_f32 v134, v134, v135
	v_cvt_pk_bf16_f32 v135, v136, v137
	v_cvt_pk_bf16_f32 v136, v130, v131
	v_cvt_pk_bf16_f32 v137, v132, v133
	global_store_dwordx4 v[208:209], v[142:145], off
	global_store_dwordx4 v[208:209], v[134:137], off offset:256
	v_and_b32_e32 v212, 0xffff0000, v160
	v_lshlrev_b32_e32 v160, 16, v160
	v_fma_f32 v126, v126, v102, v160
	v_fma_f32 v127, v127, v103, v212
	v_and_b32_e32 v212, 0xffff0000, v161
	v_lshlrev_b32_e32 v161, 16, v161
	v_fma_f32 v128, v128, v104, v161
	v_fma_f32 v129, v129, v105, v212
	v_and_b32_e32 v212, 0xffff0000, v162
	v_lshlrev_b32_e32 v162, 16, v162
	v_fma_f32 v122, v122, v98, v162
	v_fma_f32 v123, v123, v99, v212
	v_and_b32_e32 v212, 0xffff0000, v163
	v_lshlrev_b32_e32 v163, 16, v163
	v_fma_f32 v124, v124, v100, v163
	v_fma_f32 v125, v125, v101, v212
	v_cvt_pk_bf16_f32 v126, v126, v127
	v_cvt_pk_bf16_f32 v127, v128, v129
	v_cvt_pk_bf16_f32 v128, v122, v123
	v_cvt_pk_bf16_f32 v129, v124, v125
	v_and_b32_e32 v212, 0xffff0000, v164
	v_lshlrev_b32_e32 v164, 16, v164
	v_fma_f32 v118, v118, v86, v164
	v_fma_f32 v119, v119, v87, v212
	v_and_b32_e32 v212, 0xffff0000, v165
	v_lshlrev_b32_e32 v165, 16, v165
	v_fma_f32 v120, v120, v88, v165
	v_fma_f32 v121, v121, v89, v212
	v_and_b32_e32 v212, 0xffff0000, v166
	v_lshlrev_b32_e32 v166, 16, v166
	v_fma_f32 v114, v114, v82, v166
	v_fma_f32 v115, v115, v83, v212
	v_and_b32_e32 v212, 0xffff0000, v167
	v_lshlrev_b32_e32 v167, 16, v167
	v_fma_f32 v116, v116, v84, v167
	v_fma_f32 v117, v117, v85, v212
	v_cvt_pk_bf16_f32 v118, v118, v119
	v_cvt_pk_bf16_f32 v119, v120, v121
	v_cvt_pk_bf16_f32 v120, v114, v115
; __device__ __forceinline__ unsigned cvt_pk_bf16(float lo, float hi) { f32x2_t v = {lo, hi}; bf16x2_t b = __builtin_convertvector(v, bf16x2_t); return __builtin_bit_cast(unsigned, b); }
; __device__ __forceinline__ float bflo(unsigned w) { return __uint_as_float(w << 16); }
; __device__ __forceinline__ float bfhi(unsigned w) { return __uint_as_float(w & 0xffff0000u); }
;     __device__ __forceinline__ void operator()(const f32x4 (&acc)[2][2][4][2], const Unit& u, int wr, int wc, int fr, int fq) const {
;     ...
;             for (int m = 0; m < 4; ++m) { const size_t off = (size_t)(row0 + ai * HALF + m * 16) * 1024 + col0;
; #pragma unroll
;                 for (int bj = 0; bj < 2; ++bj) {
;                     f32x4 x0, x1;
;                     if (xin_f32) { x0 = *(const f32x4*)(xin_f32 + off + bj * HALF); x1 = *(const f32x4*)(xin_f32 + off + bj * HALF + 4); }
;                     else { const u32x4 w = *(const u32x4*)(xin_b + off + bj * HALF); x0 = (f32x4){bflo(w.x), bfhi(w.x), bflo(w.y), bfhi(w.y)}; x1 = (f32x4){bflo(w.z), bfhi(w.z), bflo(w.w), bfhi(w.w)}; }
;                     x0 = x0 + gv[bj][0] * acc[ai][bj][m][0]; x1 = x1 + gv[bj][1] * acc[ai][bj][m][1];
;                     if (xout_f32) { *(f32x4*)(xout_f32 + off + bj * HALF) = x0; *(f32x4*)(xout_f32 + off + bj * HALF + 4) = x1; }
;                     else { u32x4 w; w.x = cvt_pk_bf16(x0[0], x0[1]); w.y = cvt_pk_bf16(x0[2], x0[3]); w.z = cvt_pk_bf16(x1[0], x1[1]); w.w = cvt_pk_bf16(x1[2], x1[3]); *(u32x4*)(xout_b + off + bj * HALF) = w; }
	v_cvt_pk_bf16_f32 v121, v116, v117
	v_add_co_u32_e32 v250, vcc, 0x8000, v208
	v_addc_co_u32_e32 v251, vcc, 0, v209, vcc
	global_store_dwordx4 v[250:251], v[126:129], off
	global_store_dwordx4 v[250:251], v[118:121], off offset:256
	v_and_b32_e32 v212, 0xffff0000, v168
	v_lshlrev_b32_e32 v168, 16, v168
	v_fma_f32 v110, v110, v102, v168
	v_fma_f32 v111, v111, v103, v212
	v_and_b32_e32 v212, 0xffff0000, v169
	v_lshlrev_b32_e32 v169, 16, v169
	v_fma_f32 v112, v112, v104, v169
	v_fma_f32 v113, v113, v105, v212
	v_and_b32_e32 v212, 0xffff0000, v170
	v_lshlrev_b32_e32 v170, 16, v170
	v_fma_f32 v106, v106, v98, v170
	v_fma_f32 v107, v107, v99, v212
	v_and_b32_e32 v212, 0xffff0000, v171
	v_lshlrev_b32_e32 v171, 16, v171
	v_fma_f32 v108, v108, v100, v171
	v_fma_f32 v109, v109, v101, v212
	v_cvt_pk_bf16_f32 v110, v110, v111
	v_cvt_pk_bf16_f32 v111, v112, v113
	v_cvt_pk_bf16_f32 v112, v106, v107
	v_cvt_pk_bf16_f32 v113, v108, v109
	v_and_b32_e32 v212, 0xffff0000, v174
	v_lshlrev_b32_e32 v174, 16, v174
	v_fma_f32 v94, v94, v86, v174
	v_fma_f32 v95, v95, v87, v212
	v_and_b32_e32 v212, 0xffff0000, v175
	v_lshlrev_b32_e32 v175, 16, v175
	v_fma_f32 v96, v96, v88, v175
	v_fma_f32 v97, v97, v89, v212
	v_and_b32_e32 v212, 0xffff0000, v176
	v_lshlrev_b32_e32 v176, 16, v176
	v_fma_f32 v90, v90, v82, v176
	v_fma_f32 v91, v91, v83, v212
	v_and_b32_e32 v212, 0xffff0000, v177
	v_lshlrev_b32_e32 v177, 16, v177
	v_fma_f32 v92, v92, v84, v177
	v_fma_f32 v93, v93, v85, v212
	v_cvt_pk_bf16_f32 v94, v94, v95
	v_cvt_pk_bf16_f32 v95, v96, v97
	v_cvt_pk_bf16_f32 v96, v90, v91
	v_cvt_pk_bf16_f32 v97, v92, v93
	v_add_co_u32_e32 v250, vcc, 0x10000, v208
	v_addc_co_u32_e32 v251, vcc, 0, v209, vcc
	global_store_dwordx4 v[250:251], v[110:113], off
	global_store_dwordx4 v[250:251], v[94:97], off offset:256
	v_and_b32_e32 v212, 0xffff0000, v178
	v_lshlrev_b32_e32 v178, 16, v178
	v_fma_f32 v78, v78, v102, v178
	v_fma_f32 v79, v79, v103, v212
	v_and_b32_e32 v212, 0xffff0000, v179
	v_lshlrev_b32_e32 v179, 16, v179
	v_fma_f32 v80, v80, v104, v179
	v_fma_f32 v81, v81, v105, v212
	v_and_b32_e32 v212, 0xffff0000, v180
	v_lshlrev_b32_e32 v180, 16, v180
	v_fma_f32 v74, v74, v98, v180
	v_fma_f32 v75, v75, v99, v212
	v_and_b32_e32 v212, 0xffff0000, v181
	v_lshlrev_b32_e32 v181, 16, v181
	v_fma_f32 v76, v76, v100, v181
	v_fma_f32 v77, v77, v101, v212
	v_cvt_pk_bf16_f32 v78, v78, v79
	v_cvt_pk_bf16_f32 v79, v80, v81
	v_cvt_pk_bf16_f32 v80, v74, v75
	v_cvt_pk_bf16_f32 v81, v76, v77
	v_and_b32_e32 v212, 0xffff0000, v182
	v_lshlrev_b32_e32 v182, 16, v182
	v_fma_f32 v70, v70, v86, v182
	v_fma_f32 v71, v71, v87, v212
	v_and_b32_e32 v212, 0xffff0000, v183
	v_lshlrev_b32_e32 v183, 16, v183
	v_fma_f32 v72, v72, v88, v183
	v_fma_f32 v73, v73, v89, v212
	v_and_b32_e32 v212, 0xffff0000, v184
	v_lshlrev_b32_e32 v184, 16, v184
	v_fma_f32 v66, v66, v82, v184
	v_fma_f32 v67, v67, v83, v212
	v_and_b32_e32 v212, 0xffff0000, v185
	v_lshlrev_b32_e32 v185, 16, v185
	v_fma_f32 v68, v68, v84, v185
	v_fma_f32 v69, v69, v85, v212
	v_cvt_pk_bf16_f32 v70, v70, v71
	v_cvt_pk_bf16_f32 v71, v72, v73
	v_cvt_pk_bf16_f32 v72, v66, v67
	v_cvt_pk_bf16_f32 v73, v68, v69
	v_add_co_u32_e32 v250, vcc, 0x18000, v208
	v_addc_co_u32_e32 v251, vcc, 0, v209, vcc
	global_store_dwordx4 v[250:251], v[78:81], off
	global_store_dwordx4 v[250:251], v[70:73], off offset:256
	v_and_b32_e32 v212, 0xffff0000, v186
	v_lshlrev_b32_e32 v186, 16, v186
	v_fma_f32 v62, v62, v102, v186
	v_fma_f32 v63, v63, v103, v212
	v_and_b32_e32 v212, 0xffff0000, v187
	v_lshlrev_b32_e32 v187, 16, v187
	v_fma_f32 v64, v64, v104, v187
	v_fma_f32 v65, v65, v105, v212
	v_and_b32_e32 v212, 0xffff0000, v188
	v_lshlrev_b32_e32 v188, 16, v188
	v_fma_f32 v58, v58, v98, v188
	v_fma_f32 v59, v59, v99, v212
	v_and_b32_e32 v212, 0xffff0000, v189
	v_lshlrev_b32_e32 v189, 16, v189
	v_fma_f32 v60, v60, v100, v189
	v_fma_f32 v61, v61, v101, v212
	v_cvt_pk_bf16_f32 v62, v62, v63
	v_cvt_pk_bf16_f32 v63, v64, v65
	v_cvt_pk_bf16_f32 v64, v58, v59
	v_cvt_pk_bf16_f32 v65, v60, v61
	v_and_b32_e32 v212, 0xffff0000, v190
	v_lshlrev_b32_e32 v190, 16, v190
	v_fma_f32 v54, v54, v86, v190
	v_fma_f32 v55, v55, v87, v212
	v_and_b32_e32 v212, 0xffff0000, v191
	v_lshlrev_b32_e32 v191, 16, v191
	v_fma_f32 v56, v56, v88, v191
	v_fma_f32 v57, v57, v89, v212
	v_and_b32_e32 v212, 0xffff0000, v192
	v_lshlrev_b32_e32 v192, 16, v192
	v_fma_f32 v50, v50, v82, v192
	v_fma_f32 v51, v51, v83, v212
	v_and_b32_e32 v212, 0xffff0000, v193
	v_lshlrev_b32_e32 v193, 16, v193
	v_fma_f32 v52, v52, v84, v193
	v_fma_f32 v53, v53, v85, v212
	v_cvt_pk_bf16_f32 v54, v54, v55
	v_cvt_pk_bf16_f32 v55, v56, v57
	v_cvt_pk_bf16_f32 v56, v50, v51
	v_cvt_pk_bf16_f32 v57, v52, v53
	v_add_co_u32_e32 v250, vcc, 0x40000, v208
	v_addc_co_u32_e32 v251, vcc, 0, v209, vcc
	global_store_dwordx4 v[250:251], v[62:65], off
	global_store_dwordx4 v[250:251], v[54:57], off offset:256
	v_and_b32_e32 v212, 0xffff0000, v194
	v_lshlrev_b32_e32 v194, 16, v194
	v_fma_f32 v46, v46, v102, v194
	v_fma_f32 v47, v47, v103, v212
	v_and_b32_e32 v212, 0xffff0000, v195
	v_lshlrev_b32_e32 v195, 16, v195
	v_fma_f32 v48, v48, v104, v195
	v_fma_f32 v49, v49, v105, v212
	v_and_b32_e32 v212, 0xffff0000, v196
	v_lshlrev_b32_e32 v196, 16, v196
	v_fma_f32 v42, v42, v98, v196
	v_fma_f32 v43, v43, v99, v212
	v_and_b32_e32 v212, 0xffff0000, v197
	v_lshlrev_b32_e32 v197, 16, v197
	v_fma_f32 v44, v44, v100, v197
	v_fma_f32 v45, v45, v101, v212
	v_cvt_pk_bf16_f32 v46, v46, v47
	v_cvt_pk_bf16_f32 v47, v48, v49
	v_cvt_pk_bf16_f32 v48, v42, v43
	v_cvt_pk_bf16_f32 v49, v44, v45
	v_and_b32_e32 v212, 0xffff0000, v198
	v_lshlrev_b32_e32 v198, 16, v198
	v_fma_f32 v38, v38, v86, v198
; __device__ __forceinline__ unsigned cvt_pk_bf16(float lo, float hi) { f32x2_t v = {lo, hi}; bf16x2_t b = __builtin_convertvector(v, bf16x2_t); return __builtin_bit_cast(unsigned, b); }
; __device__ __forceinline__ float bflo(unsigned w) { return __uint_as_float(w << 16); }
; __device__ __forceinline__ float bfhi(unsigned w) { return __uint_as_float(w & 0xffff0000u); }
;     __device__ __forceinline__ void operator()(const f32x4 (&acc)[2][2][4][2], const Unit& u, int wr, int wc, int fr, int fq) const {
;     ...
;             for (int m = 0; m < 4; ++m) { const size_t off = (size_t)(row0 + ai * HALF + m * 16) * 1024 + col0;
; #pragma unroll
;                 for (int bj = 0; bj < 2; ++bj) {
;                     f32x4 x0, x1;
;                     if (xin_f32) { x0 = *(const f32x4*)(xin_f32 + off + bj * HALF); x1 = *(const f32x4*)(xin_f32 + off + bj * HALF + 4); }
;                     else { const u32x4 w = *(const u32x4*)(xin_b + off + bj * HALF); x0 = (f32x4){bflo(w.x), bfhi(w.x), bflo(w.y), bfhi(w.y)}; x1 = (f32x4){bflo(w.z), bfhi(w.z), bflo(w.w), bfhi(w.w)}; }
;                     x0 = x0 + gv[bj][0] * acc[ai][bj][m][0]; x1 = x1 + gv[bj][1] * acc[ai][bj][m][1];
;                     if (xout_f32) { *(f32x4*)(xout_f32 + off + bj * HALF) = x0; *(f32x4*)(xout_f32 + off + bj * HALF + 4) = x1; }
;                     else { u32x4 w; w.x = cvt_pk_bf16(x0[0], x0[1]); w.y = cvt_pk_bf16(x0[2], x0[3]); w.z = cvt_pk_bf16(x1[0], x1[1]); w.w = cvt_pk_bf16(x1[2], x1[3]); *(u32x4*)(xout_b + off + bj * HALF) = w; }
	v_fma_f32 v39, v39, v87, v212
	v_and_b32_e32 v212, 0xffff0000, v199
	v_lshlrev_b32_e32 v199, 16, v199
	v_fma_f32 v40, v40, v88, v199
	v_fma_f32 v41, v41, v89, v212
	v_and_b32_e32 v212, 0xffff0000, v200
	v_lshlrev_b32_e32 v200, 16, v200
	v_fma_f32 v34, v34, v82, v200
	v_fma_f32 v35, v35, v83, v212
	v_and_b32_e32 v212, 0xffff0000, v201
	v_lshlrev_b32_e32 v201, 16, v201
	v_fma_f32 v36, v36, v84, v201
	v_fma_f32 v37, v37, v85, v212
	v_cvt_pk_bf16_f32 v38, v38, v39
	v_cvt_pk_bf16_f32 v39, v40, v41
	v_cvt_pk_bf16_f32 v40, v34, v35
	v_cvt_pk_bf16_f32 v41, v36, v37
	v_add_co_u32_e32 v250, vcc, 0x48000, v208
	v_addc_co_u32_e32 v251, vcc, 0, v209, vcc
	global_store_dwordx4 v[250:251], v[46:49], off
	global_store_dwordx4 v[250:251], v[38:41], off offset:256
	v_and_b32_e32 v212, 0xffff0000, v218
	v_lshlrev_b32_e32 v218, 16, v218
	v_fma_f32 v30, v30, v102, v218
	v_fma_f32 v31, v31, v103, v212
	v_and_b32_e32 v212, 0xffff0000, v219
	v_lshlrev_b32_e32 v219, 16, v219
	v_fma_f32 v32, v32, v104, v219
	v_fma_f32 v33, v33, v105, v212
	v_and_b32_e32 v212, 0xffff0000, v220
	v_lshlrev_b32_e32 v220, 16, v220
	v_fma_f32 v26, v26, v98, v220
	v_fma_f32 v27, v27, v99, v212
	v_and_b32_e32 v212, 0xffff0000, v221
	v_lshlrev_b32_e32 v221, 16, v221
	v_fma_f32 v28, v28, v100, v221
	v_fma_f32 v29, v29, v101, v212
	v_cvt_pk_bf16_f32 v30, v30, v31
	v_cvt_pk_bf16_f32 v31, v32, v33
	v_cvt_pk_bf16_f32 v32, v26, v27
	v_cvt_pk_bf16_f32 v33, v28, v29
	v_and_b32_e32 v212, 0xffff0000, v222
	v_lshlrev_b32_e32 v222, 16, v222
	v_fma_f32 v22, v22, v86, v222
	v_fma_f32 v23, v23, v87, v212
	v_and_b32_e32 v212, 0xffff0000, v223
	v_lshlrev_b32_e32 v223, 16, v223
	v_fma_f32 v24, v24, v88, v223
	v_fma_f32 v25, v25, v89, v212
	v_and_b32_e32 v212, 0xffff0000, v224
	v_lshlrev_b32_e32 v224, 16, v224
	v_fma_f32 v18, v18, v82, v224
	v_fma_f32 v19, v19, v83, v212
	v_and_b32_e32 v212, 0xffff0000, v225
	v_lshlrev_b32_e32 v225, 16, v225
	v_fma_f32 v20, v20, v84, v225
	v_fma_f32 v21, v21, v85, v212
	v_cvt_pk_bf16_f32 v22, v22, v23
	v_cvt_pk_bf16_f32 v23, v24, v25
	v_cvt_pk_bf16_f32 v24, v18, v19
	v_cvt_pk_bf16_f32 v25, v20, v21
	v_add_co_u32_e32 v250, vcc, 0x50000, v208
	v_addc_co_u32_e32 v251, vcc, 0, v209, vcc
	global_store_dwordx4 v[250:251], v[30:33], off
	global_store_dwordx4 v[250:251], v[22:25], off offset:256
	v_and_b32_e32 v212, 0xffff0000, v242
	v_lshlrev_b32_e32 v242, 16, v242
	v_fma_f32 v14, v14, v102, v242
	v_fma_f32 v15, v15, v103, v212
	v_and_b32_e32 v212, 0xffff0000, v243
	v_lshlrev_b32_e32 v243, 16, v243
	v_fma_f32 v16, v16, v104, v243
	v_fma_f32 v17, v17, v105, v212
	v_and_b32_e32 v212, 0xffff0000, v244
	v_lshlrev_b32_e32 v244, 16, v244
	v_fma_f32 v10, v10, v98, v244
	v_fma_f32 v11, v11, v99, v212
	v_and_b32_e32 v212, 0xffff0000, v245
	v_lshlrev_b32_e32 v245, 16, v245
	v_fma_f32 v12, v12, v100, v245
	v_fma_f32 v13, v13, v101, v212
	v_cvt_pk_bf16_f32 v14, v14, v15
	v_cvt_pk_bf16_f32 v15, v16, v17
	v_cvt_pk_bf16_f32 v16, v10, v11
	v_cvt_pk_bf16_f32 v17, v12, v13
	v_and_b32_e32 v212, 0xffff0000, v246
	v_lshlrev_b32_e32 v246, 16, v246
	v_fma_f32 v6, v6, v86, v246
	v_fma_f32 v7, v7, v87, v212
	v_and_b32_e32 v212, 0xffff0000, v247
	v_lshlrev_b32_e32 v247, 16, v247
	v_fma_f32 v8, v8, v88, v247
	v_fma_f32 v9, v9, v89, v212
	v_and_b32_e32 v212, 0xffff0000, v248
	v_lshlrev_b32_e32 v248, 16, v248
	v_fma_f32 v2, v2, v82, v248
	v_fma_f32 v3, v3, v83, v212
	v_and_b32_e32 v212, 0xffff0000, v249
	v_lshlrev_b32_e32 v249, 16, v249
	v_fma_f32 v4, v4, v84, v249
	v_fma_f32 v5, v5, v85, v212
	v_cvt_pk_bf16_f32 v6, v6, v7
	v_cvt_pk_bf16_f32 v7, v8, v9
	v_cvt_pk_bf16_f32 v8, v2, v3
	v_cvt_pk_bf16_f32 v9, v4, v5
	v_add_co_u32_e32 v250, vcc, 0x58000, v208
	v_addc_co_u32_e32 v251, vcc, 0, v209, vcc
	global_store_dwordx4 v[250:251], v[14:17], off
	global_store_dwordx4 v[250:251], v[6:9], off offset:256
	s_branch .Ldown_epi_done
.Ldown_epi_f32:
	v_and_b32_e32 v212, 0xffff0000, v152
	v_lshlrev_b32_e32 v152, 16, v152
	v_fma_f32 v142, v142, v102, v152
	v_fma_f32 v143, v143, v103, v212
	v_and_b32_e32 v212, 0xffff0000, v153
	v_lshlrev_b32_e32 v153, 16, v153
	v_fma_f32 v144, v144, v104, v153
	v_fma_f32 v145, v145, v105, v212
	v_and_b32_e32 v212, 0xffff0000, v154
	v_lshlrev_b32_e32 v154, 16, v154
	v_fma_f32 v138, v138, v98, v154
	v_fma_f32 v139, v139, v99, v212
	v_and_b32_e32 v212, 0xffff0000, v155
	v_lshlrev_b32_e32 v155, 16, v155
	v_fma_f32 v140, v140, v100, v155
	v_fma_f32 v141, v141, v101, v212
	v_and_b32_e32 v212, 0xffff0000, v156
	v_lshlrev_b32_e32 v156, 16, v156
	v_fma_f32 v134, v134, v86, v156
	v_fma_f32 v135, v135, v87, v212
	v_and_b32_e32 v212, 0xffff0000, v157
	v_lshlrev_b32_e32 v157, 16, v157
	v_fma_f32 v136, v136, v88, v157
	v_fma_f32 v137, v137, v89, v212
	v_and_b32_e32 v212, 0xffff0000, v158
	v_lshlrev_b32_e32 v158, 16, v158
	v_fma_f32 v130, v130, v82, v158
	v_fma_f32 v131, v131, v83, v212
	v_and_b32_e32 v212, 0xffff0000, v159
	v_lshlrev_b32_e32 v159, 16, v159
	v_fma_f32 v132, v132, v84, v159
	v_fma_f32 v133, v133, v85, v212
	global_store_dwordx4 v[210:211], v[142:145], off
	global_store_dwordx4 v[210:211], v[138:141], off offset:16
	global_store_dwordx4 v[210:211], v[134:137], off offset:512
	global_store_dwordx4 v[210:211], v[130:133], off offset:528
	v_and_b32_e32 v212, 0xffff0000, v160
	v_lshlrev_b32_e32 v160, 16, v160
	v_fma_f32 v126, v126, v102, v160
	v_fma_f32 v127, v127, v103, v212
	v_and_b32_e32 v212, 0xffff0000, v161
	v_lshlrev_b32_e32 v161, 16, v161
	v_fma_f32 v128, v128, v104, v161
	v_fma_f32 v129, v129, v105, v212
	v_and_b32_e32 v212, 0xffff0000, v162
	v_lshlrev_b32_e32 v162, 16, v162
	v_fma_f32 v122, v122, v98, v162
	v_fma_f32 v123, v123, v99, v212
	v_and_b32_e32 v212, 0xffff0000, v163
; __device__ __forceinline__ unsigned cvt_pk_bf16(float lo, float hi) { f32x2_t v = {lo, hi}; bf16x2_t b = __builtin_convertvector(v, bf16x2_t); return __builtin_bit_cast(unsigned, b); }
; __device__ __forceinline__ float bflo(unsigned w) { return __uint_as_float(w << 16); }
; __device__ __forceinline__ float bfhi(unsigned w) { return __uint_as_float(w & 0xffff0000u); }
;     __device__ __forceinline__ void operator()(const f32x4 (&acc)[2][2][4][2], const Unit& u, int wr, int wc, int fr, int fq) const {
;     ...
;             for (int m = 0; m < 4; ++m) { const size_t off = (size_t)(row0 + ai * HALF + m * 16) * 1024 + col0;
; #pragma unroll
;                 for (int bj = 0; bj < 2; ++bj) {
;                     f32x4 x0, x1;
;                     if (xin_f32) { x0 = *(const f32x4*)(xin_f32 + off + bj * HALF); x1 = *(const f32x4*)(xin_f32 + off + bj * HALF + 4); }
;                     else { const u32x4 w = *(const u32x4*)(xin_b + off + bj * HALF); x0 = (f32x4){bflo(w.x), bfhi(w.x), bflo(w.y), bfhi(w.y)}; x1 = (f32x4){bflo(w.z), bfhi(w.z), bflo(w.w), bfhi(w.w)}; }
;                     x0 = x0 + gv[bj][0] * acc[ai][bj][m][0]; x1 = x1 + gv[bj][1] * acc[ai][bj][m][1];
;                     if (xout_f32) { *(f32x4*)(xout_f32 + off + bj * HALF) = x0; *(f32x4*)(xout_f32 + off + bj * HALF + 4) = x1; }
;                     else { u32x4 w; w.x = cvt_pk_bf16(x0[0], x0[1]); w.y = cvt_pk_bf16(x0[2], x0[3]); w.z = cvt_pk_bf16(x1[0], x1[1]); w.w = cvt_pk_bf16(x1[2], x1[3]); *(u32x4*)(xout_b + off + bj * HALF) = w; }
	v_lshlrev_b32_e32 v163, 16, v163
	v_fma_f32 v124, v124, v100, v163
	v_fma_f32 v125, v125, v101, v212
	v_and_b32_e32 v212, 0xffff0000, v164
	v_lshlrev_b32_e32 v164, 16, v164
	v_fma_f32 v118, v118, v86, v164
	v_fma_f32 v119, v119, v87, v212
	v_and_b32_e32 v212, 0xffff0000, v165
	v_lshlrev_b32_e32 v165, 16, v165
	v_fma_f32 v120, v120, v88, v165
	v_fma_f32 v121, v121, v89, v212
	v_and_b32_e32 v212, 0xffff0000, v166
	v_lshlrev_b32_e32 v166, 16, v166
	v_fma_f32 v114, v114, v82, v166
	v_fma_f32 v115, v115, v83, v212
	v_and_b32_e32 v212, 0xffff0000, v167
	v_lshlrev_b32_e32 v167, 16, v167
	v_fma_f32 v116, v116, v84, v167
	v_fma_f32 v117, v117, v85, v212
	v_add_co_u32_e32 v250, vcc, 0x10000, v210
	v_addc_co_u32_e32 v251, vcc, 0, v211, vcc
	global_store_dwordx4 v[250:251], v[126:129], off
	global_store_dwordx4 v[250:251], v[122:125], off offset:16
	global_store_dwordx4 v[250:251], v[118:121], off offset:512
	global_store_dwordx4 v[250:251], v[114:117], off offset:528
	v_and_b32_e32 v212, 0xffff0000, v168
	v_lshlrev_b32_e32 v168, 16, v168
	v_fma_f32 v110, v110, v102, v168
	v_fma_f32 v111, v111, v103, v212
	v_and_b32_e32 v212, 0xffff0000, v169
	v_lshlrev_b32_e32 v169, 16, v169
	v_fma_f32 v112, v112, v104, v169
	v_fma_f32 v113, v113, v105, v212
	v_and_b32_e32 v212, 0xffff0000, v170
	v_lshlrev_b32_e32 v170, 16, v170
	v_fma_f32 v106, v106, v98, v170
	v_fma_f32 v107, v107, v99, v212
	v_and_b32_e32 v212, 0xffff0000, v171
	v_lshlrev_b32_e32 v171, 16, v171
	v_fma_f32 v108, v108, v100, v171
	v_fma_f32 v109, v109, v101, v212
	v_and_b32_e32 v212, 0xffff0000, v174
	v_lshlrev_b32_e32 v174, 16, v174
	v_fma_f32 v94, v94, v86, v174
	v_fma_f32 v95, v95, v87, v212
	v_and_b32_e32 v212, 0xffff0000, v175
	v_lshlrev_b32_e32 v175, 16, v175
	v_fma_f32 v96, v96, v88, v175
	v_fma_f32 v97, v97, v89, v212
	v_and_b32_e32 v212, 0xffff0000, v176
	v_lshlrev_b32_e32 v176, 16, v176
	v_fma_f32 v90, v90, v82, v176
	v_fma_f32 v91, v91, v83, v212
	v_and_b32_e32 v212, 0xffff0000, v177
	v_lshlrev_b32_e32 v177, 16, v177
	v_fma_f32 v92, v92, v84, v177
	v_fma_f32 v93, v93, v85, v212
	v_add_co_u32_e32 v250, vcc, 0x20000, v210
	v_addc_co_u32_e32 v251, vcc, 0, v211, vcc
	global_store_dwordx4 v[250:251], v[110:113], off
	global_store_dwordx4 v[250:251], v[106:109], off offset:16
	global_store_dwordx4 v[250:251], v[94:97], off offset:512
	global_store_dwordx4 v[250:251], v[90:93], off offset:528
	v_and_b32_e32 v212, 0xffff0000, v178
	v_lshlrev_b32_e32 v178, 16, v178
	v_fma_f32 v78, v78, v102, v178
	v_fma_f32 v79, v79, v103, v212
	v_and_b32_e32 v212, 0xffff0000, v179
	v_lshlrev_b32_e32 v179, 16, v179
	v_fma_f32 v80, v80, v104, v179
	v_fma_f32 v81, v81, v105, v212
	v_and_b32_e32 v212, 0xffff0000, v180
	v_lshlrev_b32_e32 v180, 16, v180
	v_fma_f32 v74, v74, v98, v180
	v_fma_f32 v75, v75, v99, v212
	v_and_b32_e32 v212, 0xffff0000, v181
	v_lshlrev_b32_e32 v181, 16, v181
	v_fma_f32 v76, v76, v100, v181
	v_fma_f32 v77, v77, v101, v212
	v_and_b32_e32 v212, 0xffff0000, v182
	v_lshlrev_b32_e32 v182, 16, v182
	v_fma_f32 v70, v70, v86, v182
	v_fma_f32 v71, v71, v87, v212
	v_and_b32_e32 v212, 0xffff0000, v183
	v_lshlrev_b32_e32 v183, 16, v183
	v_fma_f32 v72, v72, v88, v183
	v_fma_f32 v73, v73, v89, v212
	v_and_b32_e32 v212, 0xffff0000, v184
	v_lshlrev_b32_e32 v184, 16, v184
	v_fma_f32 v66, v66, v82, v184
	v_fma_f32 v67, v67, v83, v212
	v_and_b32_e32 v212, 0xffff0000, v185
	v_lshlrev_b32_e32 v185, 16, v185
	v_fma_f32 v68, v68, v84, v185
	v_fma_f32 v69, v69, v85, v212
	v_add_co_u32_e32 v250, vcc, 0x30000, v210
	v_addc_co_u32_e32 v251, vcc, 0, v211, vcc
	global_store_dwordx4 v[250:251], v[78:81], off
	global_store_dwordx4 v[250:251], v[74:77], off offset:16
	global_store_dwordx4 v[250:251], v[70:73], off offset:512
	global_store_dwordx4 v[250:251], v[66:69], off offset:528
	v_and_b32_e32 v212, 0xffff0000, v186
	v_lshlrev_b32_e32 v186, 16, v186
	v_fma_f32 v62, v62, v102, v186
	v_fma_f32 v63, v63, v103, v212
	v_and_b32_e32 v212, 0xffff0000, v187
	v_lshlrev_b32_e32 v187, 16, v187
	v_fma_f32 v64, v64, v104, v187
	v_fma_f32 v65, v65, v105, v212
	v_and_b32_e32 v212, 0xffff0000, v188
	v_lshlrev_b32_e32 v188, 16, v188
	v_fma_f32 v58, v58, v98, v188
	v_fma_f32 v59, v59, v99, v212
	v_and_b32_e32 v212, 0xffff0000, v189
	v_lshlrev_b32_e32 v189, 16, v189
	v_fma_f32 v60, v60, v100, v189
	v_fma_f32 v61, v61, v101, v212
	v_and_b32_e32 v212, 0xffff0000, v190
	v_lshlrev_b32_e32 v190, 16, v190
	v_fma_f32 v54, v54, v86, v190
	v_fma_f32 v55, v55, v87, v212
	v_and_b32_e32 v212, 0xffff0000, v191
	v_lshlrev_b32_e32 v191, 16, v191
	v_fma_f32 v56, v56, v88, v191
	v_fma_f32 v57, v57, v89, v212
	v_and_b32_e32 v212, 0xffff0000, v192
	v_lshlrev_b32_e32 v192, 16, v192
	v_fma_f32 v50, v50, v82, v192
	v_fma_f32 v51, v51, v83, v212
	v_and_b32_e32 v212, 0xffff0000, v193
; __device__ __forceinline__ unsigned cvt_pk_bf16(float lo, float hi) { f32x2_t v = {lo, hi}; bf16x2_t b = __builtin_convertvector(v, bf16x2_t); return __builtin_bit_cast(unsigned, b); }
; #define PG8_BAR __builtin_amdgcn_s_barrier()
;     __device__ __forceinline__ void operator()(const f32x4 (&acc)[2][2][4][2], const Unit& u, int wr, int wc, int fr, int fq) const {
;     ...
;                     x0 = x0 + gv[bj][0] * acc[ai][bj][m][0]; x1 = x1 + gv[bj][1] * acc[ai][bj][m][1];
;                     if (xout_f32) { *(f32x4*)(xout_f32 + off + bj * HALF) = x0; *(f32x4*)(xout_f32 + off + bj * HALF + 4) = x1; }
;                     else { u32x4 w; w.x = cvt_pk_bf16(x0[0], x0[1]); w.y = cvt_pk_bf16(x0[2], x0[3]); w.z = cvt_pk_bf16(x1[0], x1[1]); w.w = cvt_pk_bf16(x1[2], x1[3]); *(u32x4*)(xout_b + off + bj * HALF) = w; }
; template <class Epi, class Sched>
; __device__ __forceinline__ void gemm_phase(LAS unsigned char* lds, Gemm g, Sched S, const Epi& E) {
;     ...
;         if (!has_next) break;
; #pragma unroll
;         for (int a = 0; a < 2; ++a)
; #pragma unroll
;             for (int b = 0; b < 2; ++b)
; #pragma unroll
;                 for (int m = 0; m < 4; ++m)
; #pragma unroll
;                     for (int n = 0; n < 2; ++n) acc[a][b][m][n] = (f32x4){0.f, 0.f, 0.f, 0.f};
;         cur = nxt; cA = nA; cB = nB; ++ui;
;         if (wr == 1) PG8_BAR;
	v_lshlrev_b32_e32 v193, 16, v193
	v_fma_f32 v52, v52, v84, v193
	v_fma_f32 v53, v53, v85, v212
	v_add_co_u32_e32 v250, vcc, 0x80000, v210
	v_addc_co_u32_e32 v251, vcc, 0, v211, vcc
	global_store_dwordx4 v[250:251], v[62:65], off
	global_store_dwordx4 v[250:251], v[58:61], off offset:16
	global_store_dwordx4 v[250:251], v[54:57], off offset:512
	global_store_dwordx4 v[250:251], v[50:53], off offset:528
	v_and_b32_e32 v212, 0xffff0000, v194
	v_lshlrev_b32_e32 v194, 16, v194
	v_fma_f32 v46, v46, v102, v194
	v_fma_f32 v47, v47, v103, v212
	v_and_b32_e32 v212, 0xffff0000, v195
	v_lshlrev_b32_e32 v195, 16, v195
	v_fma_f32 v48, v48, v104, v195
	v_fma_f32 v49, v49, v105, v212
	v_and_b32_e32 v212, 0xffff0000, v196
	v_lshlrev_b32_e32 v196, 16, v196
	v_fma_f32 v42, v42, v98, v196
	v_fma_f32 v43, v43, v99, v212
	v_and_b32_e32 v212, 0xffff0000, v197
	v_lshlrev_b32_e32 v197, 16, v197
	v_fma_f32 v44, v44, v100, v197
	v_fma_f32 v45, v45, v101, v212
	v_and_b32_e32 v212, 0xffff0000, v198
	v_lshlrev_b32_e32 v198, 16, v198
	v_fma_f32 v38, v38, v86, v198
	v_fma_f32 v39, v39, v87, v212
	v_and_b32_e32 v212, 0xffff0000, v199
	v_lshlrev_b32_e32 v199, 16, v199
	v_fma_f32 v40, v40, v88, v199
	v_fma_f32 v41, v41, v89, v212
	v_and_b32_e32 v212, 0xffff0000, v200
	v_lshlrev_b32_e32 v200, 16, v200
	v_fma_f32 v34, v34, v82, v200
	v_fma_f32 v35, v35, v83, v212
	v_and_b32_e32 v212, 0xffff0000, v201
	v_lshlrev_b32_e32 v201, 16, v201
	v_fma_f32 v36, v36, v84, v201
	v_fma_f32 v37, v37, v85, v212
	v_add_co_u32_e32 v250, vcc, 0x90000, v210
	v_addc_co_u32_e32 v251, vcc, 0, v211, vcc
	global_store_dwordx4 v[250:251], v[46:49], off
	global_store_dwordx4 v[250:251], v[42:45], off offset:16
	global_store_dwordx4 v[250:251], v[38:41], off offset:512
	global_store_dwordx4 v[250:251], v[34:37], off offset:528
	v_and_b32_e32 v212, 0xffff0000, v218
	v_lshlrev_b32_e32 v218, 16, v218
	v_fma_f32 v30, v30, v102, v218
	v_fma_f32 v31, v31, v103, v212
	v_and_b32_e32 v212, 0xffff0000, v219
	v_lshlrev_b32_e32 v219, 16, v219
	v_fma_f32 v32, v32, v104, v219
	v_fma_f32 v33, v33, v105, v212
	v_and_b32_e32 v212, 0xffff0000, v220
	v_lshlrev_b32_e32 v220, 16, v220
	v_fma_f32 v26, v26, v98, v220
	v_fma_f32 v27, v27, v99, v212
	v_and_b32_e32 v212, 0xffff0000, v221
	v_lshlrev_b32_e32 v221, 16, v221
	v_fma_f32 v28, v28, v100, v221
	v_fma_f32 v29, v29, v101, v212
	v_and_b32_e32 v212, 0xffff0000, v222
	v_lshlrev_b32_e32 v222, 16, v222
	v_fma_f32 v22, v22, v86, v222
	v_fma_f32 v23, v23, v87, v212
	v_and_b32_e32 v212, 0xffff0000, v223
	v_lshlrev_b32_e32 v223, 16, v223
	v_fma_f32 v24, v24, v88, v223
	v_fma_f32 v25, v25, v89, v212
	v_and_b32_e32 v212, 0xffff0000, v224
	v_lshlrev_b32_e32 v224, 16, v224
	v_fma_f32 v18, v18, v82, v224
	v_fma_f32 v19, v19, v83, v212
	v_and_b32_e32 v212, 0xffff0000, v225
	v_lshlrev_b32_e32 v225, 16, v225
	v_fma_f32 v20, v20, v84, v225
	v_fma_f32 v21, v21, v85, v212
	v_add_co_u32_e32 v250, vcc, 0xa0000, v210
	v_addc_co_u32_e32 v251, vcc, 0, v211, vcc
	global_store_dwordx4 v[250:251], v[30:33], off
	global_store_dwordx4 v[250:251], v[26:29], off offset:16
	global_store_dwordx4 v[250:251], v[22:25], off offset:512
	global_store_dwordx4 v[250:251], v[18:21], off offset:528
	v_and_b32_e32 v212, 0xffff0000, v242
	v_lshlrev_b32_e32 v242, 16, v242
	v_fma_f32 v14, v14, v102, v242
	v_fma_f32 v15, v15, v103, v212
	v_and_b32_e32 v212, 0xffff0000, v243
	v_lshlrev_b32_e32 v243, 16, v243
	v_fma_f32 v16, v16, v104, v243
	v_fma_f32 v17, v17, v105, v212
	v_and_b32_e32 v212, 0xffff0000, v244
	v_lshlrev_b32_e32 v244, 16, v244
	v_fma_f32 v10, v10, v98, v244
	v_fma_f32 v11, v11, v99, v212
	v_and_b32_e32 v212, 0xffff0000, v245
	v_lshlrev_b32_e32 v245, 16, v245
	v_fma_f32 v12, v12, v100, v245
	v_fma_f32 v13, v13, v101, v212
	v_and_b32_e32 v212, 0xffff0000, v246
	v_lshlrev_b32_e32 v246, 16, v246
	v_fma_f32 v6, v6, v86, v246
	v_fma_f32 v7, v7, v87, v212
	v_and_b32_e32 v212, 0xffff0000, v247
	v_lshlrev_b32_e32 v247, 16, v247
	v_fma_f32 v8, v8, v88, v247
	v_fma_f32 v9, v9, v89, v212
	v_and_b32_e32 v212, 0xffff0000, v248
	v_lshlrev_b32_e32 v248, 16, v248
	v_fma_f32 v2, v2, v82, v248
	v_fma_f32 v3, v3, v83, v212
	v_and_b32_e32 v212, 0xffff0000, v249
	v_lshlrev_b32_e32 v249, 16, v249
	v_fma_f32 v4, v4, v84, v249
	v_fma_f32 v5, v5, v85, v212
	v_add_co_u32_e32 v250, vcc, 0xb0000, v210
	v_addc_co_u32_e32 v251, vcc, 0, v211, vcc
	global_store_dwordx4 v[250:251], v[14:17], off
	global_store_dwordx4 v[250:251], v[10:13], off offset:16
	global_store_dwordx4 v[250:251], v[6:9], off offset:512
	global_store_dwordx4 v[250:251], v[2:5], off offset:528
.Ldown_epi_done:
.LBB0_1231:
	s_andn2_b64 vcc, exec, s[0:1]
	s_mov_b64 s[0:1], -1
	s_cbranch_vccnz .LBB0_1172
	s_andn2_b64 vcc, exec, s[10:11]
	s_cbranch_vccnz .LBB0_1171
	s_barrier
	s_branch .LBB0_1171
